# sc1 write-through also for the layer-0 weight conversion and the gate phase's residual-stream stores ahead of the layer-end device barrier
# baseline (speedup 1.0000x reference)
; #define LAS __attribute__((address_space(3)))
; __device__ __forceinline__ unsigned cvt_pk_bf16(float lo, float hi) { unsigned r; asm volatile("v_cvt_pk_bf16_f32 %0, %1, %2" : "=v"(r) : "v"(lo), "v"(hi)); return r; }
; __device__ __forceinline__ void wconv_item(const float* W, int K, int Norig, int Nphys, bf16_t* WT, const float* gA, const float* gB, int split, int mapid, LAS float* scr, int item, int lane) {
;     ...
;     for (int i = 0; i < 32; ++i) { const int kk = 2 * i + (lane >> 5), k = k0 + kk;
;         float v = wv[i];
;         if (gA) v *= (k < split ? gA[k] : gB[k - split]);
;         scr[kk * 33 + (lane & 31)] = v; }
;     asm volatile("s_waitcnt lgkmcnt(0)" ::: "memory");
;     const int c = lane & 7;
; #pragma unroll
;     for (int j = 0; j < 4; ++j) { const int n = (lane >> 3) + 8 * j; const LAS float* s = scr + (8 * c) * 33 + n;
;         u32x4 o; o.x = cvt_pk_bf16(s[0 * 33], s[1 * 33]); o.y = cvt_pk_bf16(s[2 * 33], s[3 * 33]); o.z = cvt_pk_bf16(s[4 * 33], s[5 * 33]); o.w = cvt_pk_bf16(s[6 * 33], s[7 * 33]);
;         *(u32x4*)(WT + (size_t)(n0 + n) * K + k0 + 8 * c) = o; }
;     asm volatile("s_waitcnt lgkmcnt(0)" ::: "memory");
.LBB0_10:
	v_add_u32_e32 v4, 0x400, v30
	ds_write2_b32 v4, v26, v27 offset0:8 offset1:74
	ds_write2_b32 v4, v28, v29 offset0:140 offset1:206
	s_waitcnt lgkmcnt(0)
	v_add_u32_e32 v30, s34, v46
	ds_read2_b32 v[22:23], v47 offset1:33
	v_ashrrev_i32_e32 v31, 31, v30
	s_waitcnt lgkmcnt(0)
	v_cvt_pk_bf16_f32 v22, v22, v23
	ds_read2_b32 v[24:25], v47 offset0:66 offset1:99
	v_lshl_add_u64 v[28:29], s[80:81], 1, v[20:21]
	v_lshlrev_b64 v[32:33], 11, v[30:31]
	s_waitcnt lgkmcnt(0)
	v_cvt_pk_bf16_f32 v23, v24, v25
	ds_read2_b32 v[24:25], v47 offset0:132 offset1:165
	v_lshl_add_u64 v[32:33], v[28:29], 0, v[32:33]
	s_waitcnt lgkmcnt(0)
	v_cvt_pk_bf16_f32 v24, v24, v25
	ds_read2_b32 v[26:27], v47 offset0:198 offset1:231
	s_waitcnt lgkmcnt(0)
	v_cvt_pk_bf16_f32 v25, v26, v27
	global_store_dwordx4 v[32:33], v[22:25], off sc1
	v_add_u32_e32 v32, 8, v30
	v_ashrrev_i32_e32 v33, 31, v32
	ds_read2_b32 v[26:27], v47 offset0:8 offset1:41
	s_waitcnt lgkmcnt(0)
	v_cvt_pk_bf16_f32 v22, v26, v27
	ds_read2_b32 v[24:25], v47 offset0:74 offset1:107
	v_lshlrev_b64 v[32:33], 11, v[32:33]
	s_waitcnt lgkmcnt(0)
	v_cvt_pk_bf16_f32 v23, v24, v25
	ds_read2_b32 v[24:25], v47 offset0:140 offset1:173
	v_lshl_add_u64 v[32:33], v[28:29], 0, v[32:33]
	s_waitcnt lgkmcnt(0)
	v_cvt_pk_bf16_f32 v24, v24, v25
	ds_read2_b32 v[26:27], v47 offset0:206 offset1:239
	s_waitcnt lgkmcnt(0)
	v_cvt_pk_bf16_f32 v25, v26, v27
	global_store_dwordx4 v[32:33], v[22:25], off sc1
	v_add_u32_e32 v32, 16, v30
	ds_read2_b32 v[26:27], v47 offset0:16 offset1:49
	s_waitcnt lgkmcnt(0)
	v_cvt_pk_bf16_f32 v22, v26, v27
	ds_read2_b32 v[24:25], v47 offset0:82 offset1:115
	v_ashrrev_i32_e32 v33, 31, v32
	s_waitcnt lgkmcnt(0)
	v_cvt_pk_bf16_f32 v23, v24, v25
	ds_read2_b32 v[24:25], v47 offset0:148 offset1:181
	v_lshlrev_b64 v[32:33], 11, v[32:33]
	s_waitcnt lgkmcnt(0)
	v_cvt_pk_bf16_f32 v24, v24, v25
	ds_read2_b32 v[26:27], v47 offset0:214 offset1:247
	s_waitcnt lgkmcnt(0)
	v_cvt_pk_bf16_f32 v25, v26, v27
	v_lshl_add_u64 v[32:33], v[28:29], 0, v[32:33]
	ds_read2_b32 v[26:27], v47 offset0:24 offset1:57
	global_store_dwordx4 v[32:33], v[22:25], off sc1
	v_add_u32_e32 v30, 24, v30
	v_ashrrev_i32_e32 v31, 31, v30
	s_waitcnt lgkmcnt(0)
	v_cvt_pk_bf16_f32 v22, v26, v27
	ds_read2_b32 v[24:25], v47 offset0:90 offset1:123
	s_waitcnt lgkmcnt(0)
	v_cvt_pk_bf16_f32 v23, v24, v25
	ds_read2_b32 v[24:25], v47 offset0:156 offset1:189
	s_waitcnt lgkmcnt(0)
	v_cvt_pk_bf16_f32 v24, v24, v25
	ds_read2_b32 v[26:27], v47 offset0:222 offset1:255
	v_lshlrev_b64 v[30:31], 11, v[30:31]
	s_waitcnt lgkmcnt(0)
	v_cvt_pk_bf16_f32 v25, v26, v27
	v_lshl_add_u64 v[26:27], v[28:29], 0, v[30:31]
	global_store_dwordx4 v[26:27], v[22:25], off sc1
	s_waitcnt lgkmcnt(0)

; __device__ __forceinline__ void wconv_item(const float* W, int K, int Norig, int Nphys, bf16_t* WT, const float* gA, const float* gB, int split, int mapid, LAS float* scr, int item, int lane) {
;     const int nblk = Nphys / 32, kb = item / nblk, nb = item % nblk, k0 = 64 * kb, n0 = 32 * nb;
;     const int norig = colmap(mapid, n0 + (lane & 31));
;     float wv[32];
; #pragma unroll
;     for (int i = 0; i < 32; ++i) { const int k = k0 + 2 * i + (lane >> 5); wv[i] = (norig >= 0) ? W[(size_t)k * Norig + norig] : 0.f; }
; template <class AP> __device__ __forceinline__ void convert_weights(AP a, int L, bf16_t* wb, LAS float* scr, int gw, int NGW, int lane) {
;     ...
;     for (int it = gw; it < NIT; it += NGW) {
;         int r = it;
;         if (r < I0) { wconv_item(w_in, 1024, INC, INP, wb + WO_IN, g_mix, g_mix, 1024, 0, scr, r, lane); continue; } r -= I0;
;         if (r < I1) { wconv_item(w_uq, QL, 768, 768, wb + WO_UQ, g_ql, g_ql, QL, 1, scr, r, lane); continue; } r -= I1;
;         if (r < I2) { wconv_item(w_ukv, KVL, 1024, 1024, wb + WO_UKV, g_kvl, g_kvl, KVL, 2, scr, r, lane); continue; } r -= I2;
;         if (r < I3) { wconv_item(w_o, 1024, 1024, 1024, wb + WO_O, g_oa, g_oc, 512, 3, scr, r, lane); continue; } r -= I3;
;         if (r < I4) { wconv_item(w_up, 1024, FF, FF, wb + WO_UP, g_mlp, g_mlp, 1024, 3, scr, r, lane); continue; } r -= I4;
;         if (r < I5) { wconv_item(w_dn, FF, 1024, 1024, wb + WO_DN, nullptr, nullptr, 0, 3, scr, r, lane); continue; } r -= I5;
;         if (r < I6) { wconv_item(w_g, 1024, 1024, 1024, wb + WO_G, g_ple, g_ple, 1024, 3, scr, r, lane); continue; } r -= I6;
;         wconv_item(w_ple, PLE, 1024, 1024, wb + WO_PLE, nullptr, nullptr, 0, 3, scr, r, lane);
.LBB0_12:
	s_cmpk_gt_i32 s74, 0x47f
	s_mov_b64 s[4:5], -1
	s_cbranch_scc0 .LBB0_106
	s_cmpk_gt_u32 s74, 0x50f
	s_cbranch_scc0 .LBB0_87
	s_cmpk_gt_u32 s74, 0x58f
	s_cbranch_scc0 .LBB0_68
	s_cmpk_gt_u32 s74, 0x78f
	s_cbranch_scc0 .LBB0_53
	s_cmpk_gt_u32 s74, 0xf8f
	s_cbranch_scc0 .LBB0_38
	s_cmpk_gt_u32 s74, 0x178f
	s_cbranch_scc0 .LBB0_35
	s_cmpk_gt_u32 s74, 0x198f
	s_cbranch_scc0 .LBB0_20
	s_add_i32 s4, s87, 0xfffcce00
	s_and_b32 s4, s4, 0x3e0
	s_and_b32 s5, s89, 0x1c0
	v_or_b32_e32 v4, s4, v1
	v_or_b32_e32 v24, s5, v2
	v_lshlrev_b32_e32 v4, 2, v4
	v_lshl_add_u64 v[22:23], s[6:7], 0, v[4:5]
	v_lshlrev_b32_e32 v4, 12, v24
	v_lshl_add_u64 v[22:23], v[22:23], 0, v[4:5]
	v_add_co_u32_e32 v24, vcc, 0x2000, v22
	s_lshl_b32 s34, s5, 1
	s_nop 0
	v_addc_co_u32_e32 v25, vcc, 0, v23, vcc
	v_add_co_u32_e32 v26, vcc, 0x4000, v22
	s_nop 1
	v_addc_co_u32_e32 v27, vcc, 0, v23, vcc
	v_add_co_u32_e32 v28, vcc, 0x6000, v22
	s_nop 1
	v_addc_co_u32_e32 v29, vcc, 0, v23, vcc
	v_add_co_u32_e32 v30, vcc, 0x8000, v22
	s_nop 1
	v_addc_co_u32_e32 v31, vcc, 0, v23, vcc
	v_add_co_u32_e32 v32, vcc, 0xa000, v22
	s_nop 1
	v_addc_co_u32_e32 v33, vcc, 0, v23, vcc
	v_add_co_u32_e32 v34, vcc, 0xc000, v22
	s_nop 1
	v_addc_co_u32_e32 v35, vcc, 0, v23, vcc
	v_add_co_u32_e32 v36, vcc, 0xe000, v22
	s_nop 1
	v_addc_co_u32_e32 v37, vcc, 0, v23, vcc
	global_load_dword v4, v[22:23], off
	global_load_dword v40, v[24:25], off
	global_load_dword v41, v[26:27], off
	global_load_dword v42, v[28:29], off
	global_load_dword v43, v[30:31], off
	global_load_dword v93, v[32:33], off
	global_load_dword v94, v[34:35], off
	global_load_dword v95, v[36:37], off
	v_add_co_u32_e32 v24, vcc, 0x10000, v22
	s_nop 1
	v_addc_co_u32_e32 v25, vcc, 0, v23, vcc
	v_add_co_u32_e32 v26, vcc, 0x12000, v22
	s_nop 1
	v_addc_co_u32_e32 v27, vcc, 0, v23, vcc
	v_add_co_u32_e32 v28, vcc, 0x14000, v22
	s_nop 1
	v_addc_co_u32_e32 v29, vcc, 0, v23, vcc
	v_add_co_u32_e32 v30, vcc, 0x16000, v22
	s_nop 1
	v_addc_co_u32_e32 v31, vcc, 0, v23, vcc
	v_add_co_u32_e32 v32, vcc, 0x18000, v22
	s_nop 1
	v_addc_co_u32_e32 v33, vcc, 0, v23, vcc
	v_add_co_u32_e32 v34, vcc, 0x1a000, v22
	s_nop 1
	v_addc_co_u32_e32 v35, vcc, 0, v23, vcc
	v_add_co_u32_e32 v36, vcc, 0x1c000, v22
	s_nop 1
	v_addc_co_u32_e32 v37, vcc, 0, v23, vcc
	v_add_co_u32_e32 v38, vcc, 0x1e000, v22
	s_nop 1
	v_addc_co_u32_e32 v39, vcc, 0, v23, vcc
	global_load_dword v96, v[24:25], off
	global_load_dword v97, v[26:27], off
	global_load_dword v98, v[28:29], off
	global_load_dword v99, v[30:31], off
	global_load_dword v100, v[32:33], off
	global_load_dword v101, v[34:35], off
	global_load_dword v102, v[36:37], off
	global_load_dword v103, v[38:39], off
	v_add_co_u32_e32 v24, vcc, 0x20000, v22
	s_nop 1
	v_addc_co_u32_e32 v25, vcc, 0, v23, vcc
	v_add_co_u32_e32 v26, vcc, 0x22000, v22
	s_nop 1
	v_addc_co_u32_e32 v27, vcc, 0, v23, vcc
	v_add_co_u32_e32 v28, vcc, 0x24000, v22
	s_nop 1
	v_addc_co_u32_e32 v29, vcc, 0, v23, vcc
	v_add_co_u32_e32 v30, vcc, 0x26000, v22
	s_nop 1
	v_addc_co_u32_e32 v31, vcc, 0, v23, vcc
	v_add_co_u32_e32 v32, vcc, 0x28000, v22
	s_nop 1
	v_addc_co_u32_e32 v33, vcc, 0, v23, vcc
	v_add_co_u32_e32 v34, vcc, 0x2a000, v22
	s_nop 1
	v_addc_co_u32_e32 v35, vcc, 0, v23, vcc
	v_add_co_u32_e32 v36, vcc, 0x2c000, v22
	s_nop 1
	v_addc_co_u32_e32 v37, vcc, 0, v23, vcc
	v_add_co_u32_e32 v38, vcc, 0x2e000, v22
	s_nop 1
	v_addc_co_u32_e32 v39, vcc, 0, v23, vcc
	global_load_dword v104, v[24:25], off
	global_load_dword v105, v[26:27], off
	global_load_dword v106, v[28:29], off
	global_load_dword v107, v[30:31], off
	global_load_dword v108, v[32:33], off
	global_load_dword v109, v[34:35], off
	global_load_dword v110, v[36:37], off
	s_nop 0
	global_load_dword v38, v[38:39], off
	v_add_co_u32_e32 v24, vcc, 0x30000, v22
	s_nop 1
	v_addc_co_u32_e32 v25, vcc, 0, v23, vcc
	v_add_co_u32_e32 v26, vcc, 0x32000, v22
	s_nop 1
	v_addc_co_u32_e32 v27, vcc, 0, v23, vcc
	v_add_co_u32_e32 v28, vcc, 0x34000, v22
	s_nop 1
	v_addc_co_u32_e32 v29, vcc, 0, v23, vcc
	v_add_co_u32_e32 v30, vcc, 0x36000, v22
	s_nop 1
	v_addc_co_u32_e32 v31, vcc, 0, v23, vcc
	v_add_co_u32_e32 v32, vcc, 0x38000, v22
	s_nop 1
	v_addc_co_u32_e32 v33, vcc, 0, v23, vcc
	v_add_co_u32_e32 v34, vcc, 0x3a000, v22
	s_nop 1
	v_addc_co_u32_e32 v35, vcc, 0, v23, vcc
	v_add_co_u32_e32 v36, vcc, 0x3c000, v22
	s_nop 1
	v_addc_co_u32_e32 v37, vcc, 0, v23, vcc
	v_add_co_u32_e32 v22, vcc, 0x3e000, v22
	s_nop 1
	v_addc_co_u32_e32 v23, vcc, 0, v23, vcc
	global_load_dword v24, v[24:25], off
	s_nop 0
	global_load_dword v25, v[26:27], off
	s_nop 0
	global_load_dword v26, v[28:29], off
	global_load_dword v27, v[30:31], off
	s_nop 0
	global_load_dword v28, v[32:33], off
	global_load_dword v29, v[34:35], off
	global_load_dword v30, v[36:37], off
	s_nop 0
	global_load_dword v22, v[22:23], off
	s_waitcnt vmcnt(30)
; #define LAS __attribute__((address_space(3)))
; __device__ __forceinline__ unsigned cvt_pk_bf16(float lo, float hi) { unsigned r; asm volatile("v_cvt_pk_bf16_f32 %0, %1, %2" : "=v"(r) : "v"(lo), "v"(hi)); return r; }
; __device__ __forceinline__ void wconv_item(const float* W, int K, int Norig, int Nphys, bf16_t* WT, const float* gA, const float* gB, int split, int mapid, LAS float* scr, int item, int lane) {
;     ...
;     for (int i = 0; i < 32; ++i) { const int kk = 2 * i + (lane >> 5), k = k0 + kk;
;         float v = wv[i];
;         if (gA) v *= (k < split ? gA[k] : gB[k - split]);
;         scr[kk * 33 + (lane & 31)] = v; }
;     asm volatile("s_waitcnt lgkmcnt(0)" ::: "memory");
;     const int c = lane & 7;
; #pragma unroll
;     for (int j = 0; j < 4; ++j) { const int n = (lane >> 3) + 8 * j; const LAS float* s = scr + (8 * c) * 33 + n;
;         u32x4 o; o.x = cvt_pk_bf16(s[0 * 33], s[1 * 33]); o.y = cvt_pk_bf16(s[2 * 33], s[3 * 33]); o.z = cvt_pk_bf16(s[4 * 33], s[5 * 33]); o.w = cvt_pk_bf16(s[6 * 33], s[7 * 33]);
;         *(u32x4*)(WT + (size_t)(n0 + n) * K + k0 + 8 * c) = o; }
;     asm volatile("s_waitcnt lgkmcnt(0)" ::: "memory");
	ds_write2_b32 v45, v4, v40 offset1:66
	s_waitcnt vmcnt(28)
	ds_write2_b32 v45, v41, v42 offset0:132 offset1:198
	v_add_u32_e32 v4, 0x400, v45
	s_waitcnt vmcnt(26)
	ds_write2_b32 v4, v43, v93 offset0:8 offset1:74
	s_waitcnt vmcnt(24)
	ds_write2_b32 v4, v94, v95 offset0:140 offset1:206
	v_add_u32_e32 v4, 0x800, v45
	s_waitcnt vmcnt(22)
	ds_write2_b32 v4, v96, v97 offset0:16 offset1:82
	s_waitcnt vmcnt(20)
	ds_write2_b32 v4, v98, v99 offset0:148 offset1:214
	v_add_u32_e32 v4, 0xc00, v45
	s_waitcnt vmcnt(18)
	ds_write2_b32 v4, v100, v101 offset0:24 offset1:90
	s_waitcnt vmcnt(16)
	ds_write2_b32 v4, v102, v103 offset0:156 offset1:222
	v_add_u32_e32 v4, 0x1000, v45
	s_waitcnt vmcnt(14)
	ds_write2_b32 v4, v104, v105 offset0:32 offset1:98
	s_waitcnt vmcnt(12)
	ds_write2_b32 v4, v106, v107 offset0:164 offset1:230
	v_add_u32_e32 v4, 0x1400, v45
	s_waitcnt vmcnt(10)
	ds_write2_b32 v4, v108, v109 offset0:40 offset1:106
	s_waitcnt vmcnt(8)
	ds_write2_b32 v4, v110, v38 offset0:172 offset1:238
	v_add_u32_e32 v4, 0x1800, v45
	s_waitcnt vmcnt(6)
	ds_write2_b32 v4, v24, v25 offset0:48 offset1:114
	s_waitcnt vmcnt(4)
	ds_write2_b32 v4, v26, v27 offset0:180 offset1:246
	v_add_u32_e32 v4, 0x1c00, v45
	s_waitcnt vmcnt(2)
	ds_write2_b32 v4, v28, v29 offset0:56 offset1:122
	s_waitcnt vmcnt(0)
	ds_write2_b32 v4, v30, v22 offset0:188 offset1:254
	s_waitcnt lgkmcnt(0)
	ds_read2_b32 v[22:23], v47 offset1:33
	s_waitcnt lgkmcnt(0)
	v_cvt_pk_bf16_f32 v22, v22, v23
	ds_read2_b32 v[24:25], v47 offset0:66 offset1:99
	v_or_b32_e32 v4, s4, v46
	s_waitcnt lgkmcnt(0)
	v_cvt_pk_bf16_f32 v23, v24, v25
	ds_read2_b32 v[24:25], v47 offset0:132 offset1:165
	v_lshl_add_u64 v[28:29], v[6:7], 0, s[34:35]
	v_lshlrev_b32_e32 v4, 9, v4
	s_waitcnt lgkmcnt(0)
	v_cvt_pk_bf16_f32 v24, v24, v25
	ds_read2_b32 v[26:27], v47 offset0:198 offset1:231
	s_waitcnt lgkmcnt(0)
	v_cvt_pk_bf16_f32 v25, v26, v27
	v_lshl_add_u64 v[30:31], v[28:29], 0, v[4:5]
	ds_read2_b32 v[26:27], v47 offset0:8 offset1:41
	global_store_dwordx4 v[30:31], v[22:25], off sc1
	v_or_b32_e32 v4, s4, v48
	v_lshlrev_b32_e32 v4, 9, v4
	s_waitcnt lgkmcnt(0)
	v_cvt_pk_bf16_f32 v22, v26, v27
	ds_read2_b32 v[24:25], v47 offset0:74 offset1:107
	s_waitcnt lgkmcnt(0)
	v_cvt_pk_bf16_f32 v23, v24, v25
	ds_read2_b32 v[24:25], v47 offset0:140 offset1:173
	s_waitcnt lgkmcnt(0)
	v_cvt_pk_bf16_f32 v24, v24, v25
	ds_read2_b32 v[26:27], v47 offset0:206 offset1:239
	s_waitcnt lgkmcnt(0)
	v_cvt_pk_bf16_f32 v25, v26, v27
	v_lshl_add_u64 v[30:31], v[28:29], 0, v[4:5]
	ds_read2_b32 v[26:27], v47 offset0:16 offset1:49
	global_store_dwordx4 v[30:31], v[22:25], off sc1
	v_or_b32_e32 v4, s4, v49
	v_lshlrev_b32_e32 v4, 9, v4
	s_waitcnt lgkmcnt(0)
	v_cvt_pk_bf16_f32 v22, v26, v27
	ds_read2_b32 v[24:25], v47 offset0:82 offset1:115
	s_waitcnt lgkmcnt(0)
	v_cvt_pk_bf16_f32 v23, v24, v25
	ds_read2_b32 v[24:25], v47 offset0:148 offset1:181
	s_waitcnt lgkmcnt(0)
	v_cvt_pk_bf16_f32 v24, v24, v25
	ds_read2_b32 v[26:27], v47 offset0:214 offset1:247
	s_waitcnt lgkmcnt(0)
	v_cvt_pk_bf16_f32 v25, v26, v27
	v_lshl_add_u64 v[30:31], v[28:29], 0, v[4:5]
	ds_read2_b32 v[26:27], v47 offset0:24 offset1:57
	global_store_dwordx4 v[30:31], v[22:25], off sc1
	v_or_b32_e32 v4, s4, v50
	v_lshlrev_b32_e32 v4, 9, v4
	s_waitcnt lgkmcnt(0)
	v_cvt_pk_bf16_f32 v22, v26, v27
	ds_read2_b32 v[24:25], v47 offset0:90 offset1:123
	s_waitcnt lgkmcnt(0)
	v_cvt_pk_bf16_f32 v23, v24, v25
	ds_read2_b32 v[24:25], v47 offset0:156 offset1:189
	s_waitcnt lgkmcnt(0)
	v_cvt_pk_bf16_f32 v24, v24, v25
	ds_read2_b32 v[26:27], v47 offset0:222 offset1:255
	s_waitcnt lgkmcnt(0)
	v_cvt_pk_bf16_f32 v25, v26, v27
	v_lshl_add_u64 v[26:27], v[28:29], 0, v[4:5]
	global_store_dwordx4 v[26:27], v[22:25], off sc1
	s_waitcnt lgkmcnt(0)
	s_mov_b64 s[4:5], 0

; #define LAS __attribute__((address_space(3)))
; __device__ __forceinline__ unsigned cvt_pk_bf16(float lo, float hi) { unsigned r; asm volatile("v_cvt_pk_bf16_f32 %0, %1, %2" : "=v"(r) : "v"(lo), "v"(hi)); return r; }
; __device__ __forceinline__ void wconv_item(const float* W, int K, int Norig, int Nphys, bf16_t* WT, const float* gA, const float* gB, int split, int mapid, LAS float* scr, int item, int lane) {
;     ...
;     for (int i = 0; i < 32; ++i) { const int kk = 2 * i + (lane >> 5), k = k0 + kk;
;         float v = wv[i];
;         if (gA) v *= (k < split ? gA[k] : gB[k - split]);
;         scr[kk * 33 + (lane & 31)] = v; }
;     asm volatile("s_waitcnt lgkmcnt(0)" ::: "memory");
;     const int c = lane & 7;
; #pragma unroll
;     for (int j = 0; j < 4; ++j) { const int n = (lane >> 3) + 8 * j; const LAS float* s = scr + (8 * c) * 33 + n;
;         u32x4 o; o.x = cvt_pk_bf16(s[0 * 33], s[1 * 33]); o.y = cvt_pk_bf16(s[2 * 33], s[3 * 33]); o.z = cvt_pk_bf16(s[4 * 33], s[5 * 33]); o.w = cvt_pk_bf16(s[6 * 33], s[7 * 33]);
;         *(u32x4*)(WT + (size_t)(n0 + n) * K + k0 + 8 * c) = o; }
;     asm volatile("s_waitcnt lgkmcnt(0)" ::: "memory");
.LBB0_33:
	s_waitcnt vmcnt(7)
	v_add_u32_e32 v4, v44, v80
	v_add_u32_e32 v4, 0x400, v4
	ds_write2_b32 v4, v26, v27 offset0:8 offset1:74
	ds_write2_b32 v4, v28, v29 offset0:140 offset1:206
	s_waitcnt lgkmcnt(0)
	s_waitcnt vmcnt(0)
	ds_read2_b32 v[22:23], v47 offset1:33
	s_waitcnt lgkmcnt(0)
	v_cvt_pk_bf16_f32 v22, v22, v23
	ds_read2_b32 v[24:25], v47 offset0:66 offset1:99
	s_lshl_b32 s34, s34, 1
	v_or_b32_e32 v4, s82, v46
	s_waitcnt lgkmcnt(0)
	v_cvt_pk_bf16_f32 v23, v24, v25
	ds_read2_b32 v[24:25], v47 offset0:132 offset1:165
	v_lshl_add_u64 v[28:29], v[8:9], 0, s[34:35]
	v_lshlrev_b32_e32 v4, 11, v4
	s_waitcnt lgkmcnt(0)
	v_cvt_pk_bf16_f32 v24, v24, v25
	ds_read2_b32 v[26:27], v47 offset0:198 offset1:231
	s_waitcnt lgkmcnt(0)
	v_cvt_pk_bf16_f32 v25, v26, v27
	v_lshl_add_u64 v[30:31], v[28:29], 0, v[4:5]
	ds_read2_b32 v[26:27], v47 offset0:8 offset1:41
	global_store_dwordx4 v[30:31], v[22:25], off sc1
	v_or_b32_e32 v4, s82, v48
	v_lshlrev_b32_e32 v4, 11, v4
	s_waitcnt lgkmcnt(0)
	v_cvt_pk_bf16_f32 v22, v26, v27
	ds_read2_b32 v[24:25], v47 offset0:74 offset1:107
	s_waitcnt lgkmcnt(0)
	v_cvt_pk_bf16_f32 v23, v24, v25
	ds_read2_b32 v[24:25], v47 offset0:140 offset1:173
	s_waitcnt lgkmcnt(0)
	v_cvt_pk_bf16_f32 v24, v24, v25
	ds_read2_b32 v[26:27], v47 offset0:206 offset1:239
	s_waitcnt lgkmcnt(0)
	v_cvt_pk_bf16_f32 v25, v26, v27
	v_lshl_add_u64 v[30:31], v[28:29], 0, v[4:5]
	ds_read2_b32 v[26:27], v47 offset0:16 offset1:49
	global_store_dwordx4 v[30:31], v[22:25], off sc1
	v_or_b32_e32 v4, s82, v49
	v_lshlrev_b32_e32 v4, 11, v4
	s_waitcnt lgkmcnt(0)
	v_cvt_pk_bf16_f32 v22, v26, v27
	ds_read2_b32 v[24:25], v47 offset0:82 offset1:115
	s_waitcnt lgkmcnt(0)
	v_cvt_pk_bf16_f32 v23, v24, v25
	ds_read2_b32 v[24:25], v47 offset0:148 offset1:181
	s_waitcnt lgkmcnt(0)
	v_cvt_pk_bf16_f32 v24, v24, v25
	ds_read2_b32 v[26:27], v47 offset0:214 offset1:247
	s_waitcnt lgkmcnt(0)
	v_cvt_pk_bf16_f32 v25, v26, v27
	v_lshl_add_u64 v[30:31], v[28:29], 0, v[4:5]
	ds_read2_b32 v[26:27], v47 offset0:24 offset1:57
	global_store_dwordx4 v[30:31], v[22:25], off sc1
	v_or_b32_e32 v4, s82, v50
	v_lshlrev_b32_e32 v4, 11, v4
	s_waitcnt lgkmcnt(0)
	v_cvt_pk_bf16_f32 v22, v26, v27
	ds_read2_b32 v[24:25], v47 offset0:90 offset1:123
	s_waitcnt lgkmcnt(0)
	v_cvt_pk_bf16_f32 v23, v24, v25
	ds_read2_b32 v[24:25], v47 offset0:156 offset1:189
	s_waitcnt lgkmcnt(0)
	v_cvt_pk_bf16_f32 v24, v24, v25
	ds_read2_b32 v[26:27], v47 offset0:222 offset1:255
	s_waitcnt lgkmcnt(0)
	v_cvt_pk_bf16_f32 v25, v26, v27
	v_lshl_add_u64 v[26:27], v[28:29], 0, v[4:5]
	global_store_dwordx4 v[26:27], v[22:25], off sc1
	s_waitcnt lgkmcnt(0)

; __device__ __forceinline__ void wconv_item(const float* W, int K, int Norig, int Nphys, bf16_t* WT, const float* gA, const float* gB, int split, int mapid, LAS float* scr, int item, int lane) {
;     const int nblk = Nphys / 32, kb = item / nblk, nb = item % nblk, k0 = 64 * kb, n0 = 32 * nb;
;     const int norig = colmap(mapid, n0 + (lane & 31));
;     float wv[32];
; #pragma unroll
;     for (int i = 0; i < 32; ++i) { const int k = k0 + 2 * i + (lane >> 5); wv[i] = (norig >= 0) ? W[(size_t)k * Norig + norig] : 0.f; }
.LBB0_35:
	s_andn2_b64 vcc, exec, s[4:5]
	s_cbranch_vccnz .LBB0_37
	s_add_i32 s4, s89, 0x1400
	s_and_b32 s5, s4, 0x1ffc0
	s_add_i32 s4, s87, 0xfffe0e00
	s_and_b32 s4, s4, 0x3e0
	v_or_b32_e32 v4, s4, v1
	v_or_b32_e32 v24, s5, v2
	v_lshlrev_b32_e32 v4, 2, v4
	v_lshl_add_u64 v[22:23], s[18:19], 0, v[4:5]
	v_lshlrev_b32_e32 v4, 12, v24
	v_lshl_add_u64 v[22:23], v[22:23], 0, v[4:5]
	v_add_co_u32_e32 v24, vcc, 0x2000, v22
	s_lshl_b32 s34, s5, 1
	s_nop 0
	v_addc_co_u32_e32 v25, vcc, 0, v23, vcc
	v_add_co_u32_e32 v26, vcc, 0x4000, v22
	s_nop 1
	v_addc_co_u32_e32 v27, vcc, 0, v23, vcc
	v_add_co_u32_e32 v28, vcc, 0x6000, v22
	s_nop 1
	v_addc_co_u32_e32 v29, vcc, 0, v23, vcc
	v_add_co_u32_e32 v30, vcc, 0x8000, v22
	s_nop 1
	v_addc_co_u32_e32 v31, vcc, 0, v23, vcc
	v_add_co_u32_e32 v32, vcc, 0xa000, v22
	s_nop 1
	v_addc_co_u32_e32 v33, vcc, 0, v23, vcc
	v_add_co_u32_e32 v34, vcc, 0xc000, v22
	s_nop 1
	v_addc_co_u32_e32 v35, vcc, 0, v23, vcc
	v_add_co_u32_e32 v36, vcc, 0xe000, v22
	s_nop 1
	v_addc_co_u32_e32 v37, vcc, 0, v23, vcc
	global_load_dword v4, v[22:23], off
	global_load_dword v40, v[24:25], off
	global_load_dword v41, v[26:27], off
	global_load_dword v42, v[28:29], off
	global_load_dword v43, v[30:31], off
	global_load_dword v93, v[32:33], off
	global_load_dword v94, v[34:35], off
	global_load_dword v95, v[36:37], off
	v_add_co_u32_e32 v24, vcc, 0x10000, v22
	s_nop 1
	v_addc_co_u32_e32 v25, vcc, 0, v23, vcc
	v_add_co_u32_e32 v26, vcc, 0x12000, v22
	s_nop 1
	v_addc_co_u32_e32 v27, vcc, 0, v23, vcc
	v_add_co_u32_e32 v28, vcc, 0x14000, v22
	s_nop 1
	v_addc_co_u32_e32 v29, vcc, 0, v23, vcc
	v_add_co_u32_e32 v30, vcc, 0x16000, v22
	s_nop 1
	v_addc_co_u32_e32 v31, vcc, 0, v23, vcc
	v_add_co_u32_e32 v32, vcc, 0x18000, v22
	s_nop 1
	v_addc_co_u32_e32 v33, vcc, 0, v23, vcc
	v_add_co_u32_e32 v34, vcc, 0x1a000, v22
	s_nop 1
	v_addc_co_u32_e32 v35, vcc, 0, v23, vcc
	v_add_co_u32_e32 v36, vcc, 0x1c000, v22
	s_nop 1
	v_addc_co_u32_e32 v37, vcc, 0, v23, vcc
	v_add_co_u32_e32 v38, vcc, 0x1e000, v22
	s_nop 1
	v_addc_co_u32_e32 v39, vcc, 0, v23, vcc
	global_load_dword v96, v[24:25], off
	global_load_dword v97, v[26:27], off
	global_load_dword v98, v[28:29], off
	global_load_dword v99, v[30:31], off
	global_load_dword v100, v[32:33], off
	global_load_dword v101, v[34:35], off
	global_load_dword v102, v[36:37], off
	global_load_dword v103, v[38:39], off
	v_add_co_u32_e32 v24, vcc, 0x20000, v22
	s_nop 1
	v_addc_co_u32_e32 v25, vcc, 0, v23, vcc
	v_add_co_u32_e32 v26, vcc, 0x22000, v22
	s_nop 1
	v_addc_co_u32_e32 v27, vcc, 0, v23, vcc
	v_add_co_u32_e32 v28, vcc, 0x24000, v22
	s_nop 1
	v_addc_co_u32_e32 v29, vcc, 0, v23, vcc
	v_add_co_u32_e32 v30, vcc, 0x26000, v22
	s_nop 1
	v_addc_co_u32_e32 v31, vcc, 0, v23, vcc
	v_add_co_u32_e32 v32, vcc, 0x28000, v22
	s_nop 1
	v_addc_co_u32_e32 v33, vcc, 0, v23, vcc
	v_add_co_u32_e32 v34, vcc, 0x2a000, v22
	s_nop 1
	v_addc_co_u32_e32 v35, vcc, 0, v23, vcc
	v_add_co_u32_e32 v36, vcc, 0x2c000, v22
	s_nop 1
	v_addc_co_u32_e32 v37, vcc, 0, v23, vcc
	v_add_co_u32_e32 v38, vcc, 0x2e000, v22
	s_nop 1
	v_addc_co_u32_e32 v39, vcc, 0, v23, vcc
	global_load_dword v104, v[24:25], off
	global_load_dword v105, v[26:27], off
	global_load_dword v106, v[28:29], off
	global_load_dword v107, v[30:31], off
	global_load_dword v108, v[32:33], off
	global_load_dword v109, v[34:35], off
	global_load_dword v110, v[36:37], off
	s_nop 0
	global_load_dword v38, v[38:39], off
	v_add_co_u32_e32 v24, vcc, 0x30000, v22
	s_nop 1
	v_addc_co_u32_e32 v25, vcc, 0, v23, vcc
	v_add_co_u32_e32 v26, vcc, 0x32000, v22
	s_nop 1
	v_addc_co_u32_e32 v27, vcc, 0, v23, vcc
	v_add_co_u32_e32 v28, vcc, 0x34000, v22
	s_nop 1
	v_addc_co_u32_e32 v29, vcc, 0, v23, vcc
	v_add_co_u32_e32 v30, vcc, 0x36000, v22
	s_nop 1
	v_addc_co_u32_e32 v31, vcc, 0, v23, vcc
	v_add_co_u32_e32 v32, vcc, 0x38000, v22
	s_nop 1
	v_addc_co_u32_e32 v33, vcc, 0, v23, vcc
	v_add_co_u32_e32 v34, vcc, 0x3a000, v22
	s_nop 1
	v_addc_co_u32_e32 v35, vcc, 0, v23, vcc
	v_add_co_u32_e32 v36, vcc, 0x3c000, v22
	s_nop 1
	v_addc_co_u32_e32 v37, vcc, 0, v23, vcc
	v_add_co_u32_e32 v22, vcc, 0x3e000, v22
	s_nop 1
	v_addc_co_u32_e32 v23, vcc, 0, v23, vcc
	global_load_dword v24, v[24:25], off
	s_nop 0
	global_load_dword v25, v[26:27], off
	s_nop 0
	global_load_dword v26, v[28:29], off
	global_load_dword v27, v[30:31], off
	s_nop 0
	global_load_dword v28, v[32:33], off
	global_load_dword v29, v[34:35], off
	global_load_dword v30, v[36:37], off
	s_nop 0
	global_load_dword v22, v[22:23], off
	s_waitcnt vmcnt(30)
; #define LAS __attribute__((address_space(3)))
; __device__ __forceinline__ unsigned cvt_pk_bf16(float lo, float hi) { unsigned r; asm volatile("v_cvt_pk_bf16_f32 %0, %1, %2" : "=v"(r) : "v"(lo), "v"(hi)); return r; }
; __device__ __forceinline__ void wconv_item(const float* W, int K, int Norig, int Nphys, bf16_t* WT, const float* gA, const float* gB, int split, int mapid, LAS float* scr, int item, int lane) {
;     ...
;     for (int i = 0; i < 32; ++i) { const int kk = 2 * i + (lane >> 5), k = k0 + kk;
;         float v = wv[i];
;         if (gA) v *= (k < split ? gA[k] : gB[k - split]);
;         scr[kk * 33 + (lane & 31)] = v; }
;     asm volatile("s_waitcnt lgkmcnt(0)" ::: "memory");
;     const int c = lane & 7;
; #pragma unroll
;     for (int j = 0; j < 4; ++j) { const int n = (lane >> 3) + 8 * j; const LAS float* s = scr + (8 * c) * 33 + n;
;         u32x4 o; o.x = cvt_pk_bf16(s[0 * 33], s[1 * 33]); o.y = cvt_pk_bf16(s[2 * 33], s[3 * 33]); o.z = cvt_pk_bf16(s[4 * 33], s[5 * 33]); o.w = cvt_pk_bf16(s[6 * 33], s[7 * 33]);
;         *(u32x4*)(WT + (size_t)(n0 + n) * K + k0 + 8 * c) = o; }
;     asm volatile("s_waitcnt lgkmcnt(0)" ::: "memory");
	ds_write2_b32 v45, v4, v40 offset1:66
	s_waitcnt vmcnt(28)
	ds_write2_b32 v45, v41, v42 offset0:132 offset1:198
	v_add_u32_e32 v4, 0x400, v45
	s_waitcnt vmcnt(26)
	ds_write2_b32 v4, v43, v93 offset0:8 offset1:74
	s_waitcnt vmcnt(24)
	ds_write2_b32 v4, v94, v95 offset0:140 offset1:206
	v_add_u32_e32 v4, 0x800, v45
	s_waitcnt vmcnt(22)
	ds_write2_b32 v4, v96, v97 offset0:16 offset1:82
	s_waitcnt vmcnt(20)
	ds_write2_b32 v4, v98, v99 offset0:148 offset1:214
	v_add_u32_e32 v4, 0xc00, v45
	s_waitcnt vmcnt(18)
	ds_write2_b32 v4, v100, v101 offset0:24 offset1:90
	s_waitcnt vmcnt(16)
	ds_write2_b32 v4, v102, v103 offset0:156 offset1:222
	v_add_u32_e32 v4, 0x1000, v45
	s_waitcnt vmcnt(14)
	ds_write2_b32 v4, v104, v105 offset0:32 offset1:98
	s_waitcnt vmcnt(12)
	ds_write2_b32 v4, v106, v107 offset0:164 offset1:230
	v_add_u32_e32 v4, 0x1400, v45
	s_waitcnt vmcnt(10)
	ds_write2_b32 v4, v108, v109 offset0:40 offset1:106
	s_waitcnt vmcnt(8)
	ds_write2_b32 v4, v110, v38 offset0:172 offset1:238
	v_add_u32_e32 v4, 0x1800, v45
	s_waitcnt vmcnt(6)
	ds_write2_b32 v4, v24, v25 offset0:48 offset1:114
	s_waitcnt vmcnt(4)
	ds_write2_b32 v4, v26, v27 offset0:180 offset1:246
	v_add_u32_e32 v4, 0x1c00, v45
	s_waitcnt vmcnt(2)
	ds_write2_b32 v4, v28, v29 offset0:56 offset1:122
	s_waitcnt vmcnt(0)
	ds_write2_b32 v4, v30, v22 offset0:188 offset1:254
	s_waitcnt lgkmcnt(0)
	ds_read2_b32 v[22:23], v47 offset1:33
	s_waitcnt lgkmcnt(0)
	v_cvt_pk_bf16_f32 v22, v22, v23
	ds_read2_b32 v[24:25], v47 offset0:66 offset1:99
	v_or_b32_e32 v4, s4, v46
	s_waitcnt lgkmcnt(0)
	v_cvt_pk_bf16_f32 v23, v24, v25
	ds_read2_b32 v[24:25], v47 offset0:132 offset1:165
	v_lshl_add_u64 v[28:29], v[10:11], 0, s[34:35]
	v_lshlrev_b32_e32 v4, 13, v4
	s_waitcnt lgkmcnt(0)
	v_cvt_pk_bf16_f32 v24, v24, v25
	ds_read2_b32 v[26:27], v47 offset0:198 offset1:231
	s_waitcnt lgkmcnt(0)
	v_cvt_pk_bf16_f32 v25, v26, v27
	v_lshl_add_u64 v[30:31], v[28:29], 0, v[4:5]
	ds_read2_b32 v[26:27], v47 offset0:8 offset1:41
	global_store_dwordx4 v[30:31], v[22:25], off sc1
	v_or_b32_e32 v4, s4, v48
	v_lshlrev_b32_e32 v4, 13, v4
	s_waitcnt lgkmcnt(0)
	v_cvt_pk_bf16_f32 v22, v26, v27
	ds_read2_b32 v[24:25], v47 offset0:74 offset1:107
	s_waitcnt lgkmcnt(0)
	v_cvt_pk_bf16_f32 v23, v24, v25
	ds_read2_b32 v[24:25], v47 offset0:140 offset1:173
	s_waitcnt lgkmcnt(0)
	v_cvt_pk_bf16_f32 v24, v24, v25
	ds_read2_b32 v[26:27], v47 offset0:206 offset1:239
	s_waitcnt lgkmcnt(0)
	v_cvt_pk_bf16_f32 v25, v26, v27
	v_lshl_add_u64 v[30:31], v[28:29], 0, v[4:5]
	ds_read2_b32 v[26:27], v47 offset0:16 offset1:49
	global_store_dwordx4 v[30:31], v[22:25], off sc1
	v_or_b32_e32 v4, s4, v49
	v_lshlrev_b32_e32 v4, 13, v4
	s_waitcnt lgkmcnt(0)
	v_cvt_pk_bf16_f32 v22, v26, v27
	ds_read2_b32 v[24:25], v47 offset0:82 offset1:115
	s_waitcnt lgkmcnt(0)
	v_cvt_pk_bf16_f32 v23, v24, v25
	ds_read2_b32 v[24:25], v47 offset0:148 offset1:181
	s_waitcnt lgkmcnt(0)
	v_cvt_pk_bf16_f32 v24, v24, v25
	ds_read2_b32 v[26:27], v47 offset0:214 offset1:247
	s_waitcnt lgkmcnt(0)
	v_cvt_pk_bf16_f32 v25, v26, v27
	v_lshl_add_u64 v[30:31], v[28:29], 0, v[4:5]
	ds_read2_b32 v[26:27], v47 offset0:24 offset1:57
	global_store_dwordx4 v[30:31], v[22:25], off sc1
	v_or_b32_e32 v4, s4, v50
	v_lshlrev_b32_e32 v4, 13, v4
	s_waitcnt lgkmcnt(0)
	v_cvt_pk_bf16_f32 v22, v26, v27
	ds_read2_b32 v[24:25], v47 offset0:90 offset1:123
	s_waitcnt lgkmcnt(0)
	v_cvt_pk_bf16_f32 v23, v24, v25
	ds_read2_b32 v[24:25], v47 offset0:156 offset1:189
	s_waitcnt lgkmcnt(0)
	v_cvt_pk_bf16_f32 v24, v24, v25
	ds_read2_b32 v[26:27], v47 offset0:222 offset1:255
	s_waitcnt lgkmcnt(0)
	v_cvt_pk_bf16_f32 v25, v26, v27
	v_lshl_add_u64 v[26:27], v[28:29], 0, v[4:5]
	global_store_dwordx4 v[26:27], v[22:25], off sc1
	s_waitcnt lgkmcnt(0)

; #define LAS __attribute__((address_space(3)))
; __device__ __forceinline__ unsigned cvt_pk_bf16(float lo, float hi) { unsigned r; asm volatile("v_cvt_pk_bf16_f32 %0, %1, %2" : "=v"(r) : "v"(lo), "v"(hi)); return r; }
; __device__ __forceinline__ void wconv_item(const float* W, int K, int Norig, int Nphys, bf16_t* WT, const float* gA, const float* gB, int split, int mapid, LAS float* scr, int item, int lane) {
;     ...
;     for (int i = 0; i < 32; ++i) { const int kk = 2 * i + (lane >> 5), k = k0 + kk;
;         float v = wv[i];
;         if (gA) v *= (k < split ? gA[k] : gB[k - split]);
;         scr[kk * 33 + (lane & 31)] = v; }
;     asm volatile("s_waitcnt lgkmcnt(0)" ::: "memory");
;     const int c = lane & 7;
; #pragma unroll
;     for (int j = 0; j < 4; ++j) { const int n = (lane >> 3) + 8 * j; const LAS float* s = scr + (8 * c) * 33 + n;
;         u32x4 o; o.x = cvt_pk_bf16(s[0 * 33], s[1 * 33]); o.y = cvt_pk_bf16(s[2 * 33], s[3 * 33]); o.z = cvt_pk_bf16(s[4 * 33], s[5 * 33]); o.w = cvt_pk_bf16(s[6 * 33], s[7 * 33]);
;         *(u32x4*)(WT + (size_t)(n0 + n) * K + k0 + 8 * c) = o; }
;     asm volatile("s_waitcnt lgkmcnt(0)" ::: "memory");
.LBB0_51:
	s_waitcnt vmcnt(7)
	v_add_u32_e32 v4, v44, v80
	v_add_u32_e32 v4, 0x400, v4
	ds_write2_b32 v4, v26, v27 offset0:8 offset1:74
	ds_write2_b32 v4, v28, v29 offset0:140 offset1:206
	s_waitcnt lgkmcnt(0)
	s_waitcnt vmcnt(0)
	ds_read2_b32 v[22:23], v47 offset1:33
	s_waitcnt lgkmcnt(0)
	v_cvt_pk_bf16_f32 v22, v22, v23
	ds_read2_b32 v[24:25], v47 offset0:66 offset1:99
	s_lshl_b32 s34, s34, 1
	v_or_b32_e32 v4, s82, v46
	s_waitcnt lgkmcnt(0)
	v_cvt_pk_bf16_f32 v23, v24, v25
	ds_read2_b32 v[24:25], v47 offset0:132 offset1:165
	v_lshl_add_u64 v[28:29], v[12:13], 0, s[34:35]
	v_lshlrev_b32_e32 v4, 11, v4
	s_waitcnt lgkmcnt(0)
	v_cvt_pk_bf16_f32 v24, v24, v25
	ds_read2_b32 v[26:27], v47 offset0:198 offset1:231
	s_waitcnt lgkmcnt(0)
	v_cvt_pk_bf16_f32 v25, v26, v27
	v_lshl_add_u64 v[30:31], v[28:29], 0, v[4:5]
	ds_read2_b32 v[26:27], v47 offset0:8 offset1:41
	global_store_dwordx4 v[30:31], v[22:25], off sc1
	v_or_b32_e32 v4, s82, v48
	v_lshlrev_b32_e32 v4, 11, v4
	s_waitcnt lgkmcnt(0)
	v_cvt_pk_bf16_f32 v22, v26, v27
	ds_read2_b32 v[24:25], v47 offset0:74 offset1:107
	s_waitcnt lgkmcnt(0)
	v_cvt_pk_bf16_f32 v23, v24, v25
	ds_read2_b32 v[24:25], v47 offset0:140 offset1:173
	s_waitcnt lgkmcnt(0)
	v_cvt_pk_bf16_f32 v24, v24, v25
	ds_read2_b32 v[26:27], v47 offset0:206 offset1:239
	s_waitcnt lgkmcnt(0)
	v_cvt_pk_bf16_f32 v25, v26, v27
	v_lshl_add_u64 v[30:31], v[28:29], 0, v[4:5]
	ds_read2_b32 v[26:27], v47 offset0:16 offset1:49
	global_store_dwordx4 v[30:31], v[22:25], off sc1
	v_or_b32_e32 v4, s82, v49
	v_lshlrev_b32_e32 v4, 11, v4
	s_waitcnt lgkmcnt(0)
	v_cvt_pk_bf16_f32 v22, v26, v27
	ds_read2_b32 v[24:25], v47 offset0:82 offset1:115
	s_waitcnt lgkmcnt(0)
	v_cvt_pk_bf16_f32 v23, v24, v25
	ds_read2_b32 v[24:25], v47 offset0:148 offset1:181
	s_waitcnt lgkmcnt(0)
	v_cvt_pk_bf16_f32 v24, v24, v25
	ds_read2_b32 v[26:27], v47 offset0:214 offset1:247
	s_waitcnt lgkmcnt(0)
	v_cvt_pk_bf16_f32 v25, v26, v27
	v_lshl_add_u64 v[30:31], v[28:29], 0, v[4:5]
	ds_read2_b32 v[26:27], v47 offset0:24 offset1:57
	global_store_dwordx4 v[30:31], v[22:25], off sc1
	v_or_b32_e32 v4, s82, v50
	v_lshlrev_b32_e32 v4, 11, v4
	s_waitcnt lgkmcnt(0)
	v_cvt_pk_bf16_f32 v22, v26, v27
	ds_read2_b32 v[24:25], v47 offset0:90 offset1:123
	s_waitcnt lgkmcnt(0)
	v_cvt_pk_bf16_f32 v23, v24, v25
	ds_read2_b32 v[24:25], v47 offset0:156 offset1:189
	s_waitcnt lgkmcnt(0)
	v_cvt_pk_bf16_f32 v24, v24, v25
	ds_read2_b32 v[26:27], v47 offset0:222 offset1:255
	s_waitcnt lgkmcnt(0)
	v_cvt_pk_bf16_f32 v25, v26, v27
	v_lshl_add_u64 v[26:27], v[28:29], 0, v[4:5]
	global_store_dwordx4 v[26:27], v[22:25], off sc1
	s_waitcnt lgkmcnt(0)

; #define LAS __attribute__((address_space(3)))
; __device__ __forceinline__ unsigned cvt_pk_bf16(float lo, float hi) { unsigned r; asm volatile("v_cvt_pk_bf16_f32 %0, %1, %2" : "=v"(r) : "v"(lo), "v"(hi)); return r; }
; __device__ __forceinline__ void wconv_item(const float* W, int K, int Norig, int Nphys, bf16_t* WT, const float* gA, const float* gB, int split, int mapid, LAS float* scr, int item, int lane) {
;     ...
;     for (int i = 0; i < 32; ++i) { const int kk = 2 * i + (lane >> 5), k = k0 + kk;
;         float v = wv[i];
;         if (gA) v *= (k < split ? gA[k] : gB[k - split]);
;         scr[kk * 33 + (lane & 31)] = v; }
;     asm volatile("s_waitcnt lgkmcnt(0)" ::: "memory");
;     const int c = lane & 7;
; #pragma unroll
;     for (int j = 0; j < 4; ++j) { const int n = (lane >> 3) + 8 * j; const LAS float* s = scr + (8 * c) * 33 + n;
;         u32x4 o; o.x = cvt_pk_bf16(s[0 * 33], s[1 * 33]); o.y = cvt_pk_bf16(s[2 * 33], s[3 * 33]); o.z = cvt_pk_bf16(s[4 * 33], s[5 * 33]); o.w = cvt_pk_bf16(s[6 * 33], s[7 * 33]);
;         *(u32x4*)(WT + (size_t)(n0 + n) * K + k0 + 8 * c) = o; }
;     asm volatile("s_waitcnt lgkmcnt(0)" ::: "memory");
.LBB0_66:
	v_add_u32_e32 v4, v44, v80
	v_add_u32_e32 v4, 0x400, v4
	s_waitcnt vmcnt(8)
	ds_write2_b32 v4, v26, v27 offset0:8 offset1:74
	ds_write2_b32 v4, v28, v29 offset0:140 offset1:206
	s_waitcnt lgkmcnt(0)
	s_waitcnt vmcnt(0)
	ds_read2_b32 v[22:23], v47 offset1:33
	s_waitcnt lgkmcnt(0)
	v_cvt_pk_bf16_f32 v22, v22, v23
	ds_read2_b32 v[24:25], v47 offset0:66 offset1:99
	v_or_b32_e32 v4, s82, v46
	s_waitcnt lgkmcnt(0)
	v_cvt_pk_bf16_f32 v23, v24, v25
	ds_read2_b32 v[24:25], v47 offset0:132 offset1:165
	v_lshl_add_u64 v[28:29], s[34:35], 1, v[14:15]
	v_lshlrev_b32_e32 v4, 11, v4
	s_waitcnt lgkmcnt(0)
	v_cvt_pk_bf16_f32 v24, v24, v25
	ds_read2_b32 v[26:27], v47 offset0:198 offset1:231
	s_waitcnt lgkmcnt(0)
	v_cvt_pk_bf16_f32 v25, v26, v27
	v_lshl_add_u64 v[30:31], v[28:29], 0, v[4:5]
	ds_read2_b32 v[26:27], v47 offset0:8 offset1:41
	global_store_dwordx4 v[30:31], v[22:25], off sc1
	v_or_b32_e32 v4, s82, v48
	v_lshlrev_b32_e32 v4, 11, v4
	s_waitcnt lgkmcnt(0)
	v_cvt_pk_bf16_f32 v22, v26, v27
	ds_read2_b32 v[24:25], v47 offset0:74 offset1:107
	s_waitcnt lgkmcnt(0)
	v_cvt_pk_bf16_f32 v23, v24, v25
	ds_read2_b32 v[24:25], v47 offset0:140 offset1:173
	s_waitcnt lgkmcnt(0)
	v_cvt_pk_bf16_f32 v24, v24, v25
	ds_read2_b32 v[26:27], v47 offset0:206 offset1:239
	s_waitcnt lgkmcnt(0)
	v_cvt_pk_bf16_f32 v25, v26, v27
	v_lshl_add_u64 v[30:31], v[28:29], 0, v[4:5]
	ds_read2_b32 v[26:27], v47 offset0:16 offset1:49
	global_store_dwordx4 v[30:31], v[22:25], off sc1
	v_or_b32_e32 v4, s82, v49
	v_lshlrev_b32_e32 v4, 11, v4
	s_waitcnt lgkmcnt(0)
	v_cvt_pk_bf16_f32 v22, v26, v27
	ds_read2_b32 v[24:25], v47 offset0:82 offset1:115
	s_waitcnt lgkmcnt(0)
	v_cvt_pk_bf16_f32 v23, v24, v25
	ds_read2_b32 v[24:25], v47 offset0:148 offset1:181
	s_waitcnt lgkmcnt(0)
	v_cvt_pk_bf16_f32 v24, v24, v25
	ds_read2_b32 v[26:27], v47 offset0:214 offset1:247
	s_waitcnt lgkmcnt(0)
	v_cvt_pk_bf16_f32 v25, v26, v27
	v_lshl_add_u64 v[30:31], v[28:29], 0, v[4:5]
	ds_read2_b32 v[26:27], v47 offset0:24 offset1:57
	global_store_dwordx4 v[30:31], v[22:25], off sc1
	v_or_b32_e32 v4, s82, v50
	v_lshlrev_b32_e32 v4, 11, v4
	s_waitcnt lgkmcnt(0)
	v_cvt_pk_bf16_f32 v22, v26, v27
	ds_read2_b32 v[24:25], v47 offset0:90 offset1:123
	s_waitcnt lgkmcnt(0)
	v_cvt_pk_bf16_f32 v23, v24, v25
	ds_read2_b32 v[24:25], v47 offset0:156 offset1:189
	s_waitcnt lgkmcnt(0)
	v_cvt_pk_bf16_f32 v24, v24, v25
	ds_read2_b32 v[26:27], v47 offset0:222 offset1:255
	s_waitcnt lgkmcnt(0)
	v_cvt_pk_bf16_f32 v25, v26, v27
	v_lshl_add_u64 v[26:27], v[28:29], 0, v[4:5]
	global_store_dwordx4 v[26:27], v[22:25], off sc1
	s_waitcnt lgkmcnt(0)

; #define LAS __attribute__((address_space(3)))
; __device__ __forceinline__ unsigned cvt_pk_bf16(float lo, float hi) { unsigned r; asm volatile("v_cvt_pk_bf16_f32 %0, %1, %2" : "=v"(r) : "v"(lo), "v"(hi)); return r; }
; __device__ __forceinline__ void wconv_item(const float* W, int K, int Norig, int Nphys, bf16_t* WT, const float* gA, const float* gB, int split, int mapid, LAS float* scr, int item, int lane) {
;     ...
;     for (int i = 0; i < 32; ++i) { const int kk = 2 * i + (lane >> 5), k = k0 + kk;
;         float v = wv[i];
;         if (gA) v *= (k < split ? gA[k] : gB[k - split]);
;         scr[kk * 33 + (lane & 31)] = v; }
;     asm volatile("s_waitcnt lgkmcnt(0)" ::: "memory");
;     const int c = lane & 7;
; #pragma unroll
;     for (int j = 0; j < 4; ++j) { const int n = (lane >> 3) + 8 * j; const LAS float* s = scr + (8 * c) * 33 + n;
;         u32x4 o; o.x = cvt_pk_bf16(s[0 * 33], s[1 * 33]); o.y = cvt_pk_bf16(s[2 * 33], s[3 * 33]); o.z = cvt_pk_bf16(s[4 * 33], s[5 * 33]); o.w = cvt_pk_bf16(s[6 * 33], s[7 * 33]);
;         *(u32x4*)(WT + (size_t)(n0 + n) * K + k0 + 8 * c) = o; }
;     asm volatile("s_waitcnt lgkmcnt(0)" ::: "memory");
.LBB0_85:
	s_waitcnt vmcnt(7)
	v_add_u32_e32 v4, v44, v80
	v_add_u32_e32 v4, 0x400, v4
	ds_write2_b32 v4, v26, v27 offset0:8 offset1:74
	ds_write2_b32 v4, v28, v29 offset0:140 offset1:206
	s_waitcnt lgkmcnt(0)
	s_waitcnt vmcnt(0)
	ds_read2_b32 v[22:23], v47 offset1:33
	s_waitcnt lgkmcnt(0)
	v_cvt_pk_bf16_f32 v22, v22, v23
	ds_read2_b32 v[24:25], v47 offset0:66 offset1:99
	s_lshl_b32 s34, s34, 1
	v_or_b32_e32 v4, s82, v46
	s_waitcnt lgkmcnt(0)
	v_cvt_pk_bf16_f32 v23, v24, v25
	ds_read2_b32 v[24:25], v47 offset0:132 offset1:165
	v_lshl_add_u64 v[28:29], v[16:17], 0, s[34:35]
	v_lshlrev_b32_e32 v4, 9, v4
	s_waitcnt lgkmcnt(0)
	v_cvt_pk_bf16_f32 v24, v24, v25
	ds_read2_b32 v[26:27], v47 offset0:198 offset1:231
	s_waitcnt lgkmcnt(0)
	v_cvt_pk_bf16_f32 v25, v26, v27
	v_lshl_add_u64 v[30:31], v[28:29], 0, v[4:5]
	ds_read2_b32 v[26:27], v47 offset0:8 offset1:41
	global_store_dwordx4 v[30:31], v[22:25], off sc1
	v_or_b32_e32 v4, s82, v48
	v_lshlrev_b32_e32 v4, 9, v4
	s_waitcnt lgkmcnt(0)
	v_cvt_pk_bf16_f32 v22, v26, v27
	ds_read2_b32 v[24:25], v47 offset0:74 offset1:107
	s_waitcnt lgkmcnt(0)
	v_cvt_pk_bf16_f32 v23, v24, v25
	ds_read2_b32 v[24:25], v47 offset0:140 offset1:173
	s_waitcnt lgkmcnt(0)
	v_cvt_pk_bf16_f32 v24, v24, v25
	ds_read2_b32 v[26:27], v47 offset0:206 offset1:239
	s_waitcnt lgkmcnt(0)
	v_cvt_pk_bf16_f32 v25, v26, v27
	v_lshl_add_u64 v[30:31], v[28:29], 0, v[4:5]
	ds_read2_b32 v[26:27], v47 offset0:16 offset1:49
	global_store_dwordx4 v[30:31], v[22:25], off sc1
	v_or_b32_e32 v4, s82, v49
	v_lshlrev_b32_e32 v4, 9, v4
	s_waitcnt lgkmcnt(0)
	v_cvt_pk_bf16_f32 v22, v26, v27
	ds_read2_b32 v[24:25], v47 offset0:82 offset1:115
	s_waitcnt lgkmcnt(0)
	v_cvt_pk_bf16_f32 v23, v24, v25
	ds_read2_b32 v[24:25], v47 offset0:148 offset1:181
	s_waitcnt lgkmcnt(0)
	v_cvt_pk_bf16_f32 v24, v24, v25
	ds_read2_b32 v[26:27], v47 offset0:214 offset1:247
	s_waitcnt lgkmcnt(0)
	v_cvt_pk_bf16_f32 v25, v26, v27
	v_lshl_add_u64 v[30:31], v[28:29], 0, v[4:5]
	ds_read2_b32 v[26:27], v47 offset0:24 offset1:57
	global_store_dwordx4 v[30:31], v[22:25], off sc1
	v_or_b32_e32 v4, s82, v50
	v_lshlrev_b32_e32 v4, 9, v4
	s_waitcnt lgkmcnt(0)
	v_cvt_pk_bf16_f32 v22, v26, v27
	ds_read2_b32 v[24:25], v47 offset0:90 offset1:123
	s_waitcnt lgkmcnt(0)
	v_cvt_pk_bf16_f32 v23, v24, v25
	ds_read2_b32 v[24:25], v47 offset0:156 offset1:189
	s_waitcnt lgkmcnt(0)
	v_cvt_pk_bf16_f32 v24, v24, v25
	ds_read2_b32 v[26:27], v47 offset0:222 offset1:255
	s_waitcnt lgkmcnt(0)
	v_cvt_pk_bf16_f32 v25, v26, v27
	v_lshl_add_u64 v[26:27], v[28:29], 0, v[4:5]
	global_store_dwordx4 v[26:27], v[22:25], off sc1
	s_waitcnt lgkmcnt(0)

; #define LAS __attribute__((address_space(3)))
; __device__ __forceinline__ unsigned cvt_pk_bf16(float lo, float hi) { unsigned r; asm volatile("v_cvt_pk_bf16_f32 %0, %1, %2" : "=v"(r) : "v"(lo), "v"(hi)); return r; }
; __device__ __forceinline__ void wconv_item(const float* W, int K, int Norig, int Nphys, bf16_t* WT, const float* gA, const float* gB, int split, int mapid, LAS float* scr, int item, int lane) {
;     ...
;     for (int i = 0; i < 32; ++i) { const int kk = 2 * i + (lane >> 5), k = k0 + kk;
;         float v = wv[i];
;         if (gA) v *= (k < split ? gA[k] : gB[k - split]);
;         scr[kk * 33 + (lane & 31)] = v; }
;     asm volatile("s_waitcnt lgkmcnt(0)" ::: "memory");
;     const int c = lane & 7;
; #pragma unroll
;     for (int j = 0; j < 4; ++j) { const int n = (lane >> 3) + 8 * j; const LAS float* s = scr + (8 * c) * 33 + n;
;         u32x4 o; o.x = cvt_pk_bf16(s[0 * 33], s[1 * 33]); o.y = cvt_pk_bf16(s[2 * 33], s[3 * 33]); o.z = cvt_pk_bf16(s[4 * 33], s[5 * 33]); o.w = cvt_pk_bf16(s[6 * 33], s[7 * 33]);
;         *(u32x4*)(WT + (size_t)(n0 + n) * K + k0 + 8 * c) = o; }
;     asm volatile("s_waitcnt lgkmcnt(0)" ::: "memory");
.LBB0_104:
	s_waitcnt vmcnt(7)
	v_add_u32_e32 v4, v44, v80
	v_add_u32_e32 v4, 0x400, v4
	ds_write2_b32 v4, v26, v27 offset0:8 offset1:74
	ds_write2_b32 v4, v28, v29 offset0:140 offset1:206
	s_waitcnt lgkmcnt(0)
	s_lshl_b32 s4, s34, 5
	s_waitcnt vmcnt(0)
	ds_read2_b32 v[22:23], v47 offset1:33
	v_or_b32_e32 v4, s4, v46
	s_waitcnt lgkmcnt(0)
	v_cvt_pk_bf16_f32 v22, v22, v23
	ds_read2_b32 v[24:25], v47 offset0:66 offset1:99
	s_lshl_b32 s34, s82, 1
	v_mul_u32_u24_e32 v4, 0x180, v4
	s_waitcnt lgkmcnt(0)
	v_cvt_pk_bf16_f32 v23, v24, v25
	ds_read2_b32 v[24:25], v47 offset0:132 offset1:165
	v_lshl_add_u64 v[28:29], v[18:19], 0, s[34:35]
	v_lshlrev_b32_e32 v4, 1, v4
	s_waitcnt lgkmcnt(0)
	v_cvt_pk_bf16_f32 v24, v24, v25
	ds_read2_b32 v[26:27], v47 offset0:198 offset1:231
	s_waitcnt lgkmcnt(0)
	v_cvt_pk_bf16_f32 v25, v26, v27
	v_lshl_add_u64 v[30:31], v[28:29], 0, v[4:5]
	v_or_b32_e32 v4, s4, v48
	ds_read2_b32 v[26:27], v47 offset0:8 offset1:41
	global_store_dwordx4 v[30:31], v[22:25], off sc1
	v_mul_u32_u24_e32 v4, 0x180, v4
	v_lshlrev_b32_e32 v4, 1, v4
	s_waitcnt lgkmcnt(0)
	v_cvt_pk_bf16_f32 v22, v26, v27
	ds_read2_b32 v[24:25], v47 offset0:74 offset1:107
	s_waitcnt lgkmcnt(0)
	v_cvt_pk_bf16_f32 v23, v24, v25
	ds_read2_b32 v[24:25], v47 offset0:140 offset1:173
	s_waitcnt lgkmcnt(0)
	v_cvt_pk_bf16_f32 v24, v24, v25
	ds_read2_b32 v[26:27], v47 offset0:206 offset1:239
	s_waitcnt lgkmcnt(0)
	v_cvt_pk_bf16_f32 v25, v26, v27
	v_lshl_add_u64 v[30:31], v[28:29], 0, v[4:5]
	v_or_b32_e32 v4, s4, v49
	ds_read2_b32 v[26:27], v47 offset0:16 offset1:49
	global_store_dwordx4 v[30:31], v[22:25], off sc1
	v_mul_u32_u24_e32 v4, 0x180, v4
	v_lshlrev_b32_e32 v4, 1, v4
	s_waitcnt lgkmcnt(0)
	v_cvt_pk_bf16_f32 v22, v26, v27
	ds_read2_b32 v[24:25], v47 offset0:82 offset1:115
	s_waitcnt lgkmcnt(0)
	v_cvt_pk_bf16_f32 v23, v24, v25
	ds_read2_b32 v[24:25], v47 offset0:148 offset1:181
	s_waitcnt lgkmcnt(0)
	v_cvt_pk_bf16_f32 v24, v24, v25
	ds_read2_b32 v[26:27], v47 offset0:214 offset1:247
	s_waitcnt lgkmcnt(0)
	v_cvt_pk_bf16_f32 v25, v26, v27
	v_lshl_add_u64 v[30:31], v[28:29], 0, v[4:5]
	ds_read2_b32 v[26:27], v47 offset0:24 offset1:57
	global_store_dwordx4 v[30:31], v[22:25], off sc1
	v_or_b32_e32 v4, s4, v50
	v_mul_u32_u24_e32 v4, 0x180, v4
	s_waitcnt lgkmcnt(0)
	v_cvt_pk_bf16_f32 v22, v26, v27
	ds_read2_b32 v[24:25], v47 offset0:90 offset1:123
	s_waitcnt lgkmcnt(0)
	v_cvt_pk_bf16_f32 v23, v24, v25
	ds_read2_b32 v[24:25], v47 offset0:156 offset1:189
	s_waitcnt lgkmcnt(0)
	v_cvt_pk_bf16_f32 v24, v24, v25
	ds_read2_b32 v[26:27], v47 offset0:222 offset1:255
	v_lshlrev_b32_e32 v4, 1, v4
	s_waitcnt lgkmcnt(0)
	v_cvt_pk_bf16_f32 v25, v26, v27
	v_lshl_add_u64 v[26:27], v[28:29], 0, v[4:5]
	global_store_dwordx4 v[26:27], v[22:25], off sc1
	s_waitcnt lgkmcnt(0)

; __device__ __forceinline__ float fq_sum(float s) { s += __shfl_xor(s, 16); s += __shfl_xor(s, 32); return s; }
; __device__ __forceinline__ void rstd8(float (&rs)[2][4], const float* xs, int rowb, int stride, int fq, int lim, float invn) {
;     f32x4 p[2][4];
; #pragma unroll
;     for (int ai = 0; ai < 2; ++ai)
; #pragma unroll
;         for (int m = 0; m < 4; ++m) { p[ai][m] = (f32x4){0.f, 0.f, 0.f, 0.f}; if (fq < lim) p[ai][m] = *(const f32x4*)(xs + (size_t)(rowb + ai * 128 + m * 16) * stride + fq * 4); }
; #pragma unroll
;     for (int ai = 0; ai < 2; ++ai)
; #pragma unroll
;         for (int m = 0; m < 4; ++m) rs[ai][m] = rsqrtf(fq_sum((p[ai][m][0] + p[ai][m][1]) + (p[ai][m][2] + p[ai][m][3])) * invn + EPS);
; }
;     __device__ __forceinline__ void operator()(const f32x4 (&acc)[2][2][4][2], const Unit& u, int wr, int wc, int fr, int fq) const {
;     ...
;         for (int g = 0; g < 8 / NB; ++g) {
;             u32x4 xw[NB][2], pw[NB][2];
; #pragma unroll
;             for (int k = 0; k < NB; ++k)
; #pragma unroll
;                 for (int bj = 0; bj < 2; ++bj) {
;                     const int ai = (g * NB + k) >> 2, m = (g * NB + k) & 3;
;                     const size_t off = (size_t)(u.pm * 256 + ai * 128 + wr * 64 + m * 16 + fr) * 1024 + colb + bj * 128;
;                     xw[k][bj] = *(const u32x4*)(xold + off);
;                     if (MODE == 1) pw[k][bj] = *(const u32x4*)(pg + off);
;                 }
.LBB0_1767:
	v_lshl_add_u32 v206, s44, 8, v208
	v_or_b32_e32 v200, 16, v206
	v_ashrrev_i32_e32 v207, 31, v206
	v_ashrrev_i32_e32 v201, 31, v200
	v_lshlrev_b64 v[202:203], 6, v[206:207]
	v_lshlrev_b64 v[194:195], 6, v[200:201]
	v_lshl_add_u64 v[130:131], v[152:153], 0, v[202:203]
	v_lshl_add_u64 v[134:135], v[152:153], 0, v[194:195]
	global_load_dwordx4 v[130:133], v[130:131], off
	s_nop 0
	global_load_dwordx4 v[134:137], v[134:135], off
	v_or_b32_e32 v192, 32, v206
	v_or_b32_e32 v188, 48, v206
	v_add_u32_e32 v180, 0x80, v206
	v_ashrrev_i32_e32 v193, 31, v192
	v_ashrrev_i32_e32 v189, 31, v188
	v_ashrrev_i32_e32 v181, 31, v180
	v_add_u32_e32 v176, 0x90, v206
	v_lshlrev_b64 v[190:191], 6, v[192:193]
	v_lshlrev_b64 v[182:183], 6, v[188:189]
	v_lshlrev_b64 v[178:179], 6, v[180:181]
	v_ashrrev_i32_e32 v177, 31, v176
	v_lshl_add_u64 v[138:139], v[152:153], 0, v[190:191]
	v_lshl_add_u64 v[142:143], v[152:153], 0, v[182:183]
	v_lshl_add_u64 v[158:159], v[152:153], 0, v[178:179]
	v_lshlrev_b64 v[170:171], 6, v[176:177]
	global_load_dwordx4 v[138:141], v[138:139], off
	s_nop 0
	global_load_dwordx4 v[142:145], v[142:143], off
	v_add_u32_e32 v168, 0xa0, v206
	global_load_dwordx4 v[172:175], v[158:159], off
	v_lshl_add_u64 v[158:159], v[152:153], 0, v[170:171]
	global_load_dwordx4 v[184:187], v[158:159], off
	v_ashrrev_i32_e32 v169, 31, v168
	v_add_u32_e32 v164, 0xb0, v206
	v_lshlrev_b64 v[166:167], 6, v[168:169]
	v_lshl_add_u64 v[158:159], v[152:153], 0, v[166:167]
	v_ashrrev_i32_e32 v165, 31, v164
	global_load_dwordx4 v[230:233], v[158:159], off
	v_lshlrev_b64 v[158:159], 6, v[164:165]
	v_lshl_add_u64 v[160:161], v[152:153], 0, v[158:159]
	global_load_dwordx4 v[234:237], v[160:161], off
	v_add_u32_e32 v161, 64, v216
	v_cmp_lt_i32_e32 vcc, v217, v161
	v_lshl_or_b32 v160, s38, 8, v210
	s_lshl_b32 s38, s38, 2
	v_cndmask_b32_e32 v196, v219, v217, vcc
	v_cmp_lt_i32_e32 vcc, v229, v161
	v_ashrrev_i32_e32 v161, 31, v160
	v_lshlrev_b32_e32 v213, 2, v196
	v_cndmask_b32_e32 v197, v219, v229, vcc
	v_lshlrev_b32_e32 v212, 2, v197
	v_lshlrev_b64 v[196:197], 10, v[206:207]
	v_lshl_add_u64 v[196:197], v[196:197], 0, v[160:161]
	v_lshlrev_b64 v[214:215], 1, v[196:197]
	v_lshl_add_u64 v[196:197], s[46:47], 0, v[214:215]
	v_lshl_add_u64 v[198:199], s[50:51], 0, v[214:215]
	global_load_dwordx4 v[238:241], v[196:197], off
	global_load_dwordx4 v[242:245], v[198:199], off
	v_or_b32_e32 v214, 0x100, v214
	v_lshlrev_b64 v[206:207], 11, v[206:207]
	s_ashr_i32 s39, s38, 31
	s_waitcnt vmcnt(0)
	v_mov_b32_e32 v196, v131
	v_mov_b32_e32 v197, v132
	v_mov_b32_e32 v131, v133
	v_mov_b32_e32 v132, v135
	v_mov_b32_e32 v133, v136
	v_mov_b32_e32 v135, v137
	v_pk_add_f32 v[130:131], v[196:197], v[130:131]
	v_pk_add_f32 v[132:133], v[132:133], v[134:135]
	v_mov_b32_e32 v135, v130
	v_mov_b32_e32 v134, v132
	v_mov_b32_e32 v130, v133
	v_pk_add_f32 v[130:131], v[134:135], v[130:131]
	ds_bpermute_b32 v135, v213, v131
	ds_bpermute_b32 v134, v213, v130
	v_mov_b32_e32 v136, v139
	v_mov_b32_e32 v137, v140
	s_waitcnt lgkmcnt(0)
	v_pk_add_f32 v[130:131], v[130:131], v[134:135]
	ds_bpermute_b32 v135, v212, v131
	ds_bpermute_b32 v134, v212, v130
	v_mov_b32_e32 v139, v141
	v_mov_b32_e32 v140, v143
	v_mov_b32_e32 v141, v144
	v_mov_b32_e32 v143, v145
	v_mov_b32_e32 v144, v173
	v_mov_b32_e32 v145, v174
	v_mov_b32_e32 v173, v175
	v_mov_b32_e32 v174, v185
	v_mov_b32_e32 v175, v186
	v_mov_b32_e32 v185, v187
	v_pk_add_f32 v[136:137], v[136:137], v[138:139]
	v_pk_add_f32 v[138:139], v[140:141], v[142:143]
	v_pk_add_f32 v[140:141], v[144:145], v[172:173]
	v_pk_add_f32 v[142:143], v[174:175], v[184:185]
	v_mov_b32_e32 v132, v138
	v_mov_b32_e32 v133, v136
	v_mov_b32_e32 v136, v139
	v_mov_b32_e32 v138, v142
	v_mov_b32_e32 v139, v140
	v_mov_b32_e32 v140, v143
	v_pk_add_f32 v[132:133], v[132:133], v[136:137]
	s_waitcnt lgkmcnt(0)
	v_pk_add_f32 v[130:131], v[130:131], v[134:135]
	v_pk_add_f32 v[136:137], v[138:139], v[140:141]
	ds_bpermute_b32 v139, v213, v133
	ds_bpermute_b32 v138, v213, v132
	v_pk_fma_f32 v[204:205], v[130:131], s[28:29], v[162:163] op_sel_hi:[1,0,0]
	v_mov_b32_e32 v134, v235
	v_mul_f32_e32 v130, 0x4b800000, v205
	v_cmp_gt_f32_e64 s[44:45], s31, v205
	s_waitcnt lgkmcnt(0)
	v_pk_add_f32 v[196:197], v[132:133], v[138:139]
	v_mov_b32_e32 v132, v231
	v_cndmask_b32_e64 v130, v205, v130, s[44:45]
	v_rsq_f32_e32 v130, v130
	v_mov_b32_e32 v133, v232
	v_mov_b32_e32 v231, v233
	v_mov_b32_e32 v135, v236
	v_mov_b32_e32 v235, v237
	v_pk_add_f32 v[132:133], v[132:133], v[230:231]
	v_pk_add_f32 v[134:135], v[134:135], v[234:235]
	v_mul_f32_e32 v131, 0x45800000, v130
	v_mov_b32_e32 v138, v134
	v_mov_b32_e32 v139, v132
	v_mov_b32_e32 v132, v135
	v_cndmask_b32_e64 v205, v130, v131, s[44:45]
	ds_bpermute_b32 v131, v213, v137
	ds_bpermute_b32 v130, v213, v136
	v_pk_add_f32 v[132:133], v[138:139], v[132:133]
	ds_bpermute_b32 v135, v213, v133
	ds_bpermute_b32 v134, v213, v132
	v_mul_f32_e64 v126, v205, -v126
	s_waitcnt lgkmcnt(2)
	v_pk_add_f32 v[184:185], v[136:137], v[130:131]
	v_lshl_add_u64 v[130:131], s[46:47], 0, v[214:215]
	v_mul_f32_e32 v126, 0x3fb8aa3b, v126
	s_waitcnt lgkmcnt(0)
; __device__ __forceinline__ float bf_lo(unsigned w) { return __uint_as_float(w << 16); }
; __device__ __forceinline__ float bf_hi(unsigned w) { return __uint_as_float(w & 0xffff0000u); }
; __device__ __forceinline__ float dot4(f32x4 a) { return (a[0] * a[0] + a[1] * a[1]) + (a[2] * a[2] + a[3] * a[3]); }
; __device__ __forceinline__ float fq_sum(float s) { s += __shfl_xor(s, 16); s += __shfl_xor(s, 32); return s; }
;     __device__ __forceinline__ void operator()(const f32x4 (&acc)[2][2][4][2], const Unit& u, int wr, int wc, int fr, int fq) const {
;     ...
;             for (int k = 0; k < NB; ++k) {
;                 const int ai = (g * NB + k) >> 2, m = (g * NB + k) & 3;
;                 const int row = u.pm * 256 + ai * 128 + wr * 64 + m * 16 + fr;
;                 float ss = 0.f;
; #pragma unroll
;                 for (int bj = 0; bj < 2; ++bj) {
;                     const size_t off = (size_t)row * 1024 + colb + bj * 128;
;                     const u32x4 w = xw[k][bj];
;                     const f32x4 x0 = (f32x4){bf_lo(w.x), bf_hi(w.x), bf_lo(w.y), bf_hi(w.y)}, x1 = (f32x4){bf_lo(w.z), bf_hi(w.z), bf_lo(w.w), bf_hi(w.w)};
;                     f32x4 d0 = acc[ai][bj][m][0], d1 = acc[ai][bj][m][1];
;                     if (MODE == 2) { const float r2 = rs8[ai][m] * rs8[ai][m]; d0 = d0 * r2; d1 = d1 * r2; }
;                     if (MODE == 1) {
;                         const float rs = rs8[ai][m];
;                         const u32x4 q = pw[k][bj];
;                         const f32x4 p0 = (f32x4){bf_lo(q.x), bf_hi(q.x), bf_lo(q.y), bf_hi(q.y)}, p1 = (f32x4){bf_lo(q.z), bf_hi(q.z), bf_lo(q.w), bf_hi(q.w)};
; #pragma unroll
;                         for (int i = 0; i < 4; ++i) { d0[i] = p0[i] * __builtin_amdgcn_rcpf(1.0f + __expf(-d0[i] * rs)); d1[i] = p1[i] * __builtin_amdgcn_rcpf(1.0f + __expf(-d1[i] * rs)); }
;                     }
;                     const f32x4 y0 = x0 + d0, y1 = x1 + d1;
;                     if (LAST) { *(f32x4*)(xout + off) = y0; *(f32x4*)(xout + off + 4) = y1; }
;                     else { ss += dot4(y0) + dot4(y1); *(u32x4*)(xb + off) = pack8(y0, y1); }
;                 }
;                 if (!LAST) { ss = fq_sum(ss); if (fq == 0) xs_out[(size_t)row * 16 + u.pn * 4 + wc] = ss; }
;             }
	v_pk_add_f32 v[172:173], v[132:133], v[134:135]
	v_lshl_add_u64 v[132:133], s[50:51], 0, v[214:215]
	global_load_dwordx4 v[230:233], v[130:131], off
	global_load_dwordx4 v[234:237], v[132:133], off
	v_lshlrev_b64 v[130:131], 10, v[200:201]
	v_lshl_add_u64 v[130:131], v[130:131], 0, v[160:161]
	v_lshlrev_b64 v[130:131], 1, v[130:131]
	v_lshl_add_u64 v[132:133], s[46:47], 0, v[130:131]
	v_lshl_add_u64 v[134:135], s[50:51], 0, v[130:131]
	v_or_b32_e32 v130, 0x100, v130
	global_load_dwordx4 v[142:145], v[132:133], off
	global_load_dwordx4 v[138:141], v[134:135], off
	v_lshl_add_u64 v[132:133], s[46:47], 0, v[130:131]
	v_lshl_add_u64 v[130:131], s[50:51], 0, v[130:131]
	global_load_dwordx4 v[134:137], v[132:133], off
	s_nop 0
	global_load_dwordx4 v[130:133], v[130:131], off
	v_mul_f32_e64 v122, v205, -v122
	v_exp_f32_e32 v126, v126
	v_mul_f32_e32 v122, 0x3fb8aa3b, v122
	v_exp_f32_e32 v246, v122
	v_mul_f32_e64 v122, v205, -v127
	v_mul_f32_e64 v124, v205, -v124
	v_add_f32_e32 v126, 1.0, v126
	v_mul_f32_e32 v122, 0x3fb8aa3b, v122
	v_mul_f32_e32 v124, 0x3fb8aa3b, v124
	v_exp_f32_e32 v127, v122
	v_rcp_f32_e32 v122, v126
	v_add_f32_e32 v126, 1.0, v246
	v_lshlrev_b32_e32 v246, 16, v242
	v_and_b32_e32 v247, 0xffff0000, v242
	v_mul_f32_e64 v128, v205, -v128
	v_exp_f32_e32 v242, v124
	v_mul_f32_e64 v124, v205, -v129
	v_mul_f32_e64 v123, v205, -v123
	v_mul_f32_e32 v128, 0x3fb8aa3b, v128
	v_mul_f32_e32 v124, 0x3fb8aa3b, v124
	v_mul_f32_e32 v123, 0x3fb8aa3b, v123
	v_exp_f32_e32 v128, v128
	v_exp_f32_e32 v129, v124
	v_exp_f32_e32 v248, v123
	v_mul_f32_e64 v125, v205, -v125
	v_add_f32_e32 v127, 1.0, v127
	v_add_f32_e32 v128, 1.0, v128
	v_add_f32_e32 v129, 1.0, v129
	v_mul_f32_e32 v125, 0x3fb8aa3b, v125
	v_rcp_f32_e32 v123, v127
	v_add_f32_e32 v127, 1.0, v248
	v_lshlrev_b32_e32 v248, 16, v244
	v_and_b32_e32 v249, 0xffff0000, v244
	v_rcp_f32_e32 v124, v128
	v_exp_f32_e32 v244, v125
	v_rcp_f32_e32 v125, v129
	v_rcp_f32_e32 v126, v126
	v_rcp_f32_e32 v127, v127
	v_lshlrev_b32_e32 v214, 16, v238
	v_and_b32_e32 v215, 0xffff0000, v238
	v_lshlrev_b32_e32 v222, 16, v239
	v_and_b32_e32 v223, 0xffff0000, v239
	v_add_f32_e32 v128, 1.0, v242
	v_lshlrev_b32_e32 v242, 16, v243
	v_and_b32_e32 v243, 0xffff0000, v243
	v_pk_fma_f32 v[124:125], v[124:125], v[242:243], v[222:223]
	v_pk_fma_f32 v[122:123], v[122:123], v[246:247], v[214:215]
	v_lshlrev_b32_e32 v238, 16, v240
	v_and_b32_e32 v239, 0xffff0000, v240
	v_add_f32_e32 v129, 1.0, v244
	v_mul_f32_e32 v214, v123, v123
	v_mul_f32_e32 v215, v125, v125
	v_mul_f32_e64 v118, v205, -v118
	v_rcp_f32_e32 v128, v128
	v_rcp_f32_e32 v129, v129
	v_pk_fma_f32 v[126:127], v[126:127], v[248:249], v[238:239]
	v_fmac_f32_e32 v214, v122, v122
	v_fmac_f32_e32 v215, v124, v124
	v_mul_f32_e32 v118, 0x3fb8aa3b, v118
	v_mul_f32_e64 v114, v205, -v114
	v_add_f32_e32 v214, v214, v215
	v_mul_f32_e32 v215, v127, v127
	v_exp_f32_e32 v118, v118
	v_mul_f32_e32 v114, 0x3fb8aa3b, v114
	v_fmac_f32_e32 v215, v126, v126
	v_cvt_pk_bf16_f32 v122, v122, v123
	v_cvt_pk_bf16_f32 v123, v124, v125
	v_cvt_pk_bf16_f32 v124, v126, v127
	s_waitcnt vmcnt(5)
	v_lshlrev_b32_e32 v126, 16, v230
	v_and_b32_e32 v127, 0xffff0000, v230
	v_exp_f32_e32 v230, v114
	v_lshlrev_b32_e32 v240, 16, v241
	v_and_b32_e32 v241, 0xffff0000, v241
	v_lshlrev_b32_e32 v244, 16, v245
	v_and_b32_e32 v245, 0xffff0000, v245
	v_pk_fma_f32 v[128:129], v[128:129], v[244:245], v[240:241]
	v_mul_f32_e64 v114, v205, -v119
	v_mul_f32_e64 v116, v205, -v116
	v_mul_f32_e32 v222, v129, v129
	v_add_f32_e32 v118, 1.0, v118
	v_mul_f32_e32 v114, 0x3fb8aa3b, v114
	v_mul_f32_e32 v116, 0x3fb8aa3b, v116
	v_fmac_f32_e32 v222, v128, v128
	v_cvt_pk_bf16_f32 v125, v128, v129
	v_lshlrev_b32_e32 v128, 16, v231
	v_and_b32_e32 v129, 0xffff0000, v231
	v_exp_f32_e32 v119, v114
	v_rcp_f32_e32 v114, v118
	v_add_f32_e32 v118, 1.0, v230
	s_waitcnt vmcnt(4)
	v_lshlrev_b32_e32 v230, 16, v234
	v_and_b32_e32 v231, 0xffff0000, v234
	v_mul_f32_e64 v120, v205, -v120
	v_exp_f32_e32 v234, v116
	v_mul_f32_e64 v116, v205, -v121
	v_mul_f32_e32 v120, 0x3fb8aa3b, v120
	v_mul_f32_e32 v116, 0x3fb8aa3b, v116
	v_mul_f32_e64 v115, v205, -v115
	v_exp_f32_e32 v120, v120
	v_exp_f32_e32 v121, v116
	v_mul_f32_e64 v117, v205, -v117
	v_add_f32_e32 v215, v215, v222
	v_mul_f32_e32 v115, 0x3fb8aa3b, v115
	v_mul_f32_e32 v117, 0x3fb8aa3b, v117
	v_add_f32_e32 v238, v214, v215
	v_lshlrev_b32_e32 v214, 16, v232
	v_and_b32_e32 v215, 0xffff0000, v232
	v_exp_f32_e32 v232, v115
	v_exp_f32_e32 v205, v117
	v_add_f32_e32 v119, 1.0, v119
	v_add_f32_e32 v120, 1.0, v120
	v_add_f32_e32 v121, 1.0, v121
	v_rcp_f32_e32 v115, v119
	v_rcp_f32_e32 v116, v120
	v_rcp_f32_e32 v117, v121
	v_add_f32_e32 v119, 1.0, v232
	v_add_f32_e32 v120, 1.0, v234
	v_add_f32_e32 v121, 1.0, v205
	v_rcp_f32_e32 v118, v118
	v_rcp_f32_e32 v119, v119
	v_rcp_f32_e32 v120, v120
	v_rcp_f32_e32 v121, v121
	v_lshlrev_b32_e32 v234, 16, v235
	v_and_b32_e32 v235, 0xffff0000, v235
	v_pk_fma_f32 v[128:129], v[116:117], v[234:235], v[128:129]
	v_pk_fma_f32 v[114:115], v[114:115], v[230:231], v[126:127]
	v_lshlrev_b32_e32 v222, 16, v233
	v_and_b32_e32 v223, 0xffff0000, v233
	v_lshlrev_b32_e32 v232, 16, v236
	v_and_b32_e32 v233, 0xffff0000, v236
	v_lshlrev_b32_e32 v236, 16, v237
	v_and_b32_e32 v237, 0xffff0000, v237
	v_mul_f32_e32 v116, v115, v115
	v_mul_f32_e32 v117, v129, v129
	v_pk_fma_f32 v[120:121], v[120:121], v[236:237], v[222:223]
	v_pk_fma_f32 v[118:119], v[118:119], v[232:233], v[214:215]
	v_fmac_f32_e32 v116, v114, v114
	v_fmac_f32_e32 v117, v128, v128
	v_add_f32_e32 v116, v116, v117
	v_mul_f32_e32 v117, v119, v119
	v_mul_f32_e32 v126, v121, v121
	v_fmac_f32_e32 v117, v118, v118
	v_fmac_f32_e32 v126, v120, v120
	v_add_f32_e32 v117, v117, v126
	v_add_f32_e32 v116, v116, v117
	v_add_f32_e32 v205, v238, v116
	ds_bpermute_b32 v214, v213, v205
	v_lshl_add_u64 v[116:117], s[52:53], 0, v[206:207]
	v_lshl_add_u64 v[126:127], v[160:161], 1, v[116:117]
	global_store_dwordx4 v[126:127], v[122:125], off sc1
	v_cvt_pk_bf16_f32 v116, v114, v115
	s_waitcnt lgkmcnt(0)
	v_add_f32_e32 v114, v205, v214
	ds_bpermute_b32 v199, v212, v197
	ds_bpermute_b32 v198, v212, v196
	ds_bpermute_b32 v187, v212, v185
	ds_bpermute_b32 v186, v212, v184
	ds_bpermute_b32 v175, v212, v173
	ds_bpermute_b32 v174, v212, v172
	ds_bpermute_b32 v115, v212, v114
	v_cmp_gt_f32_e32 vcc, s31, v204
	v_cvt_pk_bf16_f32 v117, v128, v129
	v_cvt_pk_bf16_f32 v118, v118, v119
	v_cvt_pk_bf16_f32 v119, v120, v121
	global_store_dwordx4 v[126:127], v[116:119], off offset:256 sc1
	s_and_saveexec_b64 s[44:45], s[40:41]
	s_cbranch_execz .LBB0_1769
	v_lshl_add_u64 v[116:117], s[18:19], 0, v[202:203]
	v_lshl_add_u64 v[116:117], s[38:39], 2, v[116:117]
	s_lshl_b32 s48, s91, 2
	v_lshl_add_u64 v[116:117], v[116:117], 0, s[48:49]
	s_waitcnt lgkmcnt(0)
	v_add_f32_e32 v114, v114, v115
	global_store_dword v[116:117], v114, off
; __device__ __forceinline__ float bf_lo(unsigned w) { return __uint_as_float(w << 16); }
; __device__ __forceinline__ float bf_hi(unsigned w) { return __uint_as_float(w & 0xffff0000u); }
; __device__ __forceinline__ float dot4(f32x4 a) { return (a[0] * a[0] + a[1] * a[1]) + (a[2] * a[2] + a[3] * a[3]); }
; __device__ __forceinline__ float fq_sum(float s) { s += __shfl_xor(s, 16); s += __shfl_xor(s, 32); return s; }
;     __device__ __forceinline__ void operator()(const f32x4 (&acc)[2][2][4][2], const Unit& u, int wr, int wc, int fr, int fq) const {
;     ...
;             for (int k = 0; k < NB; ++k) {
;                 const int ai = (g * NB + k) >> 2, m = (g * NB + k) & 3;
;                 const int row = u.pm * 256 + ai * 128 + wr * 64 + m * 16 + fr;
;                 float ss = 0.f;
; #pragma unroll
;                 for (int bj = 0; bj < 2; ++bj) {
;                     const size_t off = (size_t)row * 1024 + colb + bj * 128;
;                     const u32x4 w = xw[k][bj];
;                     const f32x4 x0 = (f32x4){bf_lo(w.x), bf_hi(w.x), bf_lo(w.y), bf_hi(w.y)}, x1 = (f32x4){bf_lo(w.z), bf_hi(w.z), bf_lo(w.w), bf_hi(w.w)};
;                     f32x4 d0 = acc[ai][bj][m][0], d1 = acc[ai][bj][m][1];
;                     if (MODE == 2) { const float r2 = rs8[ai][m] * rs8[ai][m]; d0 = d0 * r2; d1 = d1 * r2; }
;                     if (MODE == 1) {
;                         const float rs = rs8[ai][m];
;                         const u32x4 q = pw[k][bj];
;                         const f32x4 p0 = (f32x4){bf_lo(q.x), bf_hi(q.x), bf_lo(q.y), bf_hi(q.y)}, p1 = (f32x4){bf_lo(q.z), bf_hi(q.z), bf_lo(q.w), bf_hi(q.w)};
; #pragma unroll
;                         for (int i = 0; i < 4; ++i) { d0[i] = p0[i] * __builtin_amdgcn_rcpf(1.0f + __expf(-d0[i] * rs)); d1[i] = p1[i] * __builtin_amdgcn_rcpf(1.0f + __expf(-d1[i] * rs)); }
;                     }
;                     const f32x4 y0 = x0 + d0, y1 = x1 + d1;
;                     if (LAST) { *(f32x4*)(xout + off) = y0; *(f32x4*)(xout + off + 4) = y1; }
;                     else { ss += dot4(y0) + dot4(y1); *(u32x4*)(xb + off) = pack8(y0, y1); }
;                 }
;                 if (!LAST) { ss = fq_sum(ss); if (fq == 0) xs_out[(size_t)row * 16 + u.pn * 4 + wc] = ss; }
;             }
.LBB0_1769:
	s_or_b64 exec, exec, s[44:45]
	v_mul_f32_e32 v114, 0x4b800000, v204
	v_cndmask_b32_e32 v114, v204, v114, vcc
	v_rsq_f32_e32 v118, v114
	s_waitcnt vmcnt(5)
	v_lshlrev_b32_e32 v116, 16, v142
	v_and_b32_e32 v117, 0xffff0000, v142
	s_waitcnt vmcnt(4)
	v_and_b32_e32 v125, 0xffff0000, v138
	v_mul_f32_e32 v119, 0x45800000, v118
	v_cndmask_b32_e32 v142, v118, v119, vcc
	v_mul_f32_e64 v106, v142, -v106
	v_mul_f32_e32 v106, 0x3fb8aa3b, v106
	v_mul_f32_e64 v110, v142, -v110
	v_exp_f32_e32 v124, v106
	v_mul_f32_e64 v106, v142, -v111
	v_mul_f32_e32 v110, 0x3fb8aa3b, v110
	v_mul_f32_e32 v106, 0x3fb8aa3b, v106
	v_mul_f32_e64 v107, v142, -v107
	v_exp_f32_e32 v110, v110
	v_exp_f32_e32 v111, v106
	v_mul_f32_e32 v107, 0x3fb8aa3b, v107
	v_mul_f32_e64 v108, v142, -v108
	v_exp_f32_e32 v126, v107
	v_mul_f32_e32 v108, 0x3fb8aa3b, v108
	v_mul_f32_e64 v112, v142, -v112
	v_exp_f32_e32 v128, v108
	v_mul_f32_e64 v108, v142, -v113
	v_mul_f32_e32 v112, 0x3fb8aa3b, v112
	v_mul_f32_e32 v108, 0x3fb8aa3b, v108
	v_mul_f32_e64 v109, v142, -v109
	v_add_f32_e32 v110, 1.0, v110
	v_add_f32_e32 v111, 1.0, v111
	v_exp_f32_e32 v112, v112
	v_exp_f32_e32 v113, v108
	v_mul_f32_e32 v109, 0x3fb8aa3b, v109
	v_rcp_f32_e32 v106, v110
	v_add_f32_e32 v110, 1.0, v124
	v_rcp_f32_e32 v107, v111
	v_lshlrev_b32_e32 v124, 16, v138
	v_add_f32_e32 v111, 1.0, v126
	v_exp_f32_e32 v138, v109
	v_rcp_f32_e32 v110, v110
	v_rcp_f32_e32 v111, v111
	v_add_f32_e32 v112, 1.0, v112
	v_add_f32_e32 v113, 1.0, v113
	v_mul_f32_e64 v98, v142, -v98
	v_mul_f32_e64 v100, v142, -v100
	v_lshlrev_b32_e32 v120, 16, v144
	v_and_b32_e32 v121, 0xffff0000, v144
	v_lshlrev_b32_e32 v126, 16, v140
	v_and_b32_e32 v127, 0xffff0000, v140
	v_rcp_f32_e32 v108, v112
	v_add_f32_e32 v112, 1.0, v128
	v_rcp_f32_e32 v109, v113
	v_add_f32_e32 v113, 1.0, v138
	v_mul_f32_e32 v98, 0x3fb8aa3b, v98
	v_mul_f32_e32 v100, 0x3fb8aa3b, v100
	v_rcp_f32_e32 v112, v112
	v_rcp_f32_e32 v113, v113
	v_pk_fma_f32 v[106:107], v[106:107], v[124:125], v[116:117]
	v_pk_fma_f32 v[110:111], v[110:111], v[126:127], v[120:121]
	v_mul_f32_e64 v102, v142, -v102
	v_exp_f32_e32 v120, v98
	v_mul_f32_e64 v98, v142, -v103
	v_mul_f32_e64 v104, v142, -v104
	v_exp_f32_e32 v124, v100
	v_mul_f32_e64 v100, v142, -v105
	v_mul_f32_e32 v102, 0x3fb8aa3b, v102
	v_mul_f32_e32 v98, 0x3fb8aa3b, v98
	v_mul_f32_e32 v104, 0x3fb8aa3b, v104
	v_mul_f32_e32 v100, 0x3fb8aa3b, v100
	v_exp_f32_e32 v102, v102
	v_exp_f32_e32 v103, v98
	v_mul_f32_e64 v99, v142, -v99
	v_exp_f32_e32 v104, v104
	v_exp_f32_e32 v105, v100
	v_mul_f32_e64 v101, v142, -v101
	v_lshlrev_b32_e32 v122, 16, v145
	v_and_b32_e32 v123, 0xffff0000, v145
	v_lshlrev_b32_e32 v128, 16, v139
	v_and_b32_e32 v129, 0xffff0000, v139
	v_lshlrev_b32_e32 v138, 16, v141
	v_and_b32_e32 v139, 0xffff0000, v141
	v_mul_f32_e32 v99, 0x3fb8aa3b, v99
	v_mul_f32_e32 v101, 0x3fb8aa3b, v101
	v_pk_fma_f32 v[112:113], v[112:113], v[138:139], v[122:123]
	v_exp_f32_e32 v122, v99
	v_exp_f32_e32 v126, v101
	v_lshlrev_b32_e32 v118, 16, v143
	v_and_b32_e32 v119, 0xffff0000, v143
	v_pk_fma_f32 v[108:109], v[108:109], v[128:129], v[118:119]
	v_add_f32_e32 v102, 1.0, v102
	v_add_f32_e32 v103, 1.0, v103
	v_add_f32_e32 v104, 1.0, v104
	v_add_f32_e32 v105, 1.0, v105
	v_mul_f32_e32 v116, v107, v107
	v_mul_f32_e32 v117, v109, v109
	v_rcp_f32_e32 v98, v102
	v_rcp_f32_e32 v99, v103
	v_rcp_f32_e32 v100, v104
	v_rcp_f32_e32 v101, v105
	v_fmac_f32_e32 v116, v106, v106
	v_fmac_f32_e32 v117, v108, v108
	v_add_f32_e32 v102, 1.0, v120
	v_add_f32_e32 v103, 1.0, v122
	v_add_f32_e32 v104, 1.0, v124
	v_add_f32_e32 v105, 1.0, v126
	v_add_f32_e32 v116, v116, v117
	v_mul_f32_e32 v117, v111, v111
	v_mul_f32_e32 v118, v113, v113
	v_rcp_f32_e32 v102, v102
	v_rcp_f32_e32 v103, v103
	v_rcp_f32_e32 v104, v104
	v_rcp_f32_e32 v105, v105
	v_fmac_f32_e32 v117, v110, v110
	v_fmac_f32_e32 v118, v112, v112
	v_cvt_pk_bf16_f32 v106, v106, v107
	v_cvt_pk_bf16_f32 v107, v108, v109
	v_cvt_pk_bf16_f32 v108, v110, v111
	v_cvt_pk_bf16_f32 v109, v112, v113
	s_waitcnt vmcnt(3)
	v_lshlrev_b32_e32 v110, 16, v134
	v_and_b32_e32 v111, 0xffff0000, v134
	v_lshlrev_b32_e32 v112, 16, v135
	v_and_b32_e32 v113, 0xffff0000, v135
	s_waitcnt vmcnt(2)
	v_lshlrev_b32_e32 v120, 16, v130
	v_and_b32_e32 v121, 0xffff0000, v130
	v_lshlrev_b32_e32 v124, 16, v131
	v_and_b32_e32 v125, 0xffff0000, v131
	v_add_f32_e32 v117, v117, v118
	v_pk_fma_f32 v[112:113], v[100:101], v[124:125], v[112:113]
	v_pk_fma_f32 v[98:99], v[98:99], v[120:121], v[110:111]
	v_add_f32_e32 v128, v116, v117
	v_lshlrev_b32_e32 v116, 16, v136
	v_and_b32_e32 v117, 0xffff0000, v136
	v_lshlrev_b32_e32 v118, 16, v137
	v_and_b32_e32 v119, 0xffff0000, v137
	v_lshlrev_b32_e32 v122, 16, v132
	v_and_b32_e32 v123, 0xffff0000, v132
	v_lshlrev_b32_e32 v126, 16, v133
	v_and_b32_e32 v127, 0xffff0000, v133
	v_mul_f32_e32 v100, v99, v99
	v_mul_f32_e32 v101, v113, v113
	v_pk_fma_f32 v[104:105], v[104:105], v[126:127], v[118:119]
	v_pk_fma_f32 v[102:103], v[102:103], v[122:123], v[116:117]
	v_fmac_f32_e32 v100, v98, v98
	v_fmac_f32_e32 v101, v112, v112
	v_add_f32_e32 v100, v100, v101
	v_mul_f32_e32 v101, v103, v103
	v_mul_f32_e32 v110, v105, v105
	v_fmac_f32_e32 v101, v102, v102
	v_fmac_f32_e32 v110, v104, v104
	v_add_f32_e32 v101, v101, v110
	v_add_f32_e32 v100, v100, v101
	v_add_f32_e32 v116, v128, v100
	ds_bpermute_b32 v117, v213, v116
	s_waitcnt lgkmcnt(1)
	v_lshlrev_b64 v[114:115], 11, v[200:201]
	v_lshl_add_u64 v[100:101], s[52:53], 0, v[114:115]
	v_lshl_add_u64 v[110:111], v[160:161], 1, v[100:101]
	global_store_dwordx4 v[110:111], v[106:109], off sc1
	v_cvt_pk_bf16_f32 v100, v98, v99
	s_waitcnt lgkmcnt(0)
	v_add_f32_e32 v98, v116, v117
	ds_bpermute_b32 v99, v212, v98
	v_cvt_pk_bf16_f32 v101, v112, v113
	v_cvt_pk_bf16_f32 v102, v102, v103
	v_cvt_pk_bf16_f32 v103, v104, v105
	global_store_dwordx4 v[110:111], v[100:103], off offset:256 sc1
	s_and_saveexec_b64 s[44:45], s[40:41]
	s_cbranch_execz .LBB0_1771
	v_lshl_add_u64 v[100:101], s[18:19], 0, v[194:195]
	v_lshl_add_u64 v[100:101], s[38:39], 2, v[100:101]
	s_lshl_b32 s48, s91, 2
	v_lshl_add_u64 v[100:101], v[100:101], 0, s[48:49]
	s_waitcnt lgkmcnt(0)
	v_add_f32_e32 v98, v98, v99
	global_store_dword v[100:101], v98, off
;     __device__ __forceinline__ void operator()(const f32x4 (&acc)[2][2][4][2], const Unit& u, int wr, int wc, int fr, int fq) const {
;     ...
;         for (int g = 0; g < 8 / NB; ++g) {
;             u32x4 xw[NB][2], pw[NB][2];
; #pragma unroll
;             for (int k = 0; k < NB; ++k)
; #pragma unroll
;                 for (int bj = 0; bj < 2; ++bj) {
;                     const int ai = (g * NB + k) >> 2, m = (g * NB + k) & 3;
;                     const size_t off = (size_t)(u.pm * 256 + ai * 128 + wr * 64 + m * 16 + fr) * 1024 + colb + bj * 128;
;                     xw[k][bj] = *(const u32x4*)(xold + off);
;                     if (MODE == 1) pw[k][bj] = *(const u32x4*)(pg + off);
;                 }
; #pragma unroll
;             for (int k = 0; k < NB; ++k) {
;                 const int ai = (g * NB + k) >> 2, m = (g * NB + k) & 3;
;                 const int row = u.pm * 256 + ai * 128 + wr * 64 + m * 16 + fr;
;                 float ss = 0.f;
; #pragma unroll
;                 for (int bj = 0; bj < 2; ++bj) {
;                     const size_t off = (size_t)row * 1024 + colb + bj * 128;
;                     const u32x4 w = xw[k][bj];
;                     const f32x4 x0 = (f32x4){bf_lo(w.x), bf_hi(w.x), bf_lo(w.y), bf_hi(w.y)}, x1 = (f32x4){bf_lo(w.z), bf_hi(w.z), bf_lo(w.w), bf_hi(w.w)};
;                     f32x4 d0 = acc[ai][bj][m][0], d1 = acc[ai][bj][m][1];
;                     if (MODE == 2) { const float r2 = rs8[ai][m] * rs8[ai][m]; d0 = d0 * r2; d1 = d1 * r2; }
;                     if (MODE == 1) {
;                         const float rs = rs8[ai][m];
;                         const u32x4 q = pw[k][bj];
;                         const f32x4 p0 = (f32x4){bf_lo(q.x), bf_hi(q.x), bf_lo(q.y), bf_hi(q.y)}, p1 = (f32x4){bf_lo(q.z), bf_hi(q.z), bf_lo(q.w), bf_hi(q.w)};
; #pragma unroll
;                         for (int i = 0; i < 4; ++i) { d0[i] = p0[i] * __builtin_amdgcn_rcpf(1.0f + __expf(-d0[i] * rs)); d1[i] = p1[i] * __builtin_amdgcn_rcpf(1.0f + __expf(-d1[i] * rs)); }
;                     }
;                     const f32x4 y0 = x0 + d0, y1 = x1 + d1;
;                     if (LAST) { *(f32x4*)(xout + off) = y0; *(f32x4*)(xout + off + 4) = y1; }
;                     else { ss += dot4(y0) + dot4(y1); *(u32x4*)(xb + off) = pack8(y0, y1); }
;                 }
.LBB0_1771:
	s_or_b64 exec, exec, s[44:45]
	s_waitcnt lgkmcnt(0)
	v_lshlrev_b64 v[98:99], 10, v[192:193]
	v_lshl_add_u64 v[98:99], v[98:99], 0, v[160:161]
	v_lshlrev_b64 v[98:99], 1, v[98:99]
	v_lshl_add_u64 v[100:101], s[46:47], 0, v[98:99]
	global_load_dwordx4 v[118:121], v[100:101], off
	v_lshl_add_u64 v[100:101], s[50:51], 0, v[98:99]
	global_load_dwordx4 v[122:125], v[100:101], off
	v_pk_add_f32 v[100:101], v[196:197], v[198:199]
	v_lshlrev_b64 v[102:103], 10, v[188:189]
	v_pk_fma_f32 v[114:115], v[100:101], s[28:29], v[162:163] op_sel_hi:[1,0,0]
	v_lshl_add_u64 v[100:101], v[102:103], 0, v[160:161]
	v_mul_f32_e32 v102, 0x4b800000, v115
	v_lshlrev_b64 v[100:101], 1, v[100:101]
	v_cmp_gt_f32_e64 s[44:45], s31, v115
	v_or_b32_e32 v98, 0x100, v98
	v_lshl_add_u64 v[104:105], s[50:51], 0, v[100:101]
	v_cndmask_b32_e64 v106, v115, v102, s[44:45]
	v_lshl_add_u64 v[102:103], s[46:47], 0, v[100:101]
	v_or_b32_e32 v100, 0x100, v100
	v_rsq_f32_e32 v115, v106
	v_lshl_add_u64 v[126:127], s[46:47], 0, v[98:99]
	v_lshl_add_u64 v[98:99], s[50:51], 0, v[98:99]
	global_load_dwordx4 v[110:113], v[102:103], off
	global_load_dwordx4 v[106:109], v[104:105], off
	v_lshl_add_u64 v[102:103], s[46:47], 0, v[100:101]
	v_lshl_add_u64 v[100:101], s[50:51], 0, v[100:101]
	global_load_dwordx4 v[126:129], v[126:127], off
	s_nop 0
	global_load_dwordx4 v[130:133], v[98:99], off
	s_nop 0
	global_load_dwordx4 v[102:105], v[102:103], off
	s_nop 0
	global_load_dwordx4 v[98:101], v[100:101], off
	v_mul_f32_e32 v134, 0x45800000, v115
	v_cndmask_b32_e64 v115, v115, v134, s[44:45]
	v_mul_f32_e64 v94, v115, -v94
	v_mul_f32_e64 v90, v115, -v90
	v_mul_f32_e64 v95, v115, -v95
	v_mul_f32_e64 v96, v115, -v96
	v_mul_f32_e64 v97, v115, -v97
	v_mul_f32_e64 v91, v115, -v91
	v_mul_f32_e64 v92, v115, -v92
	v_mul_f32_e32 v94, 0x3fb8aa3b, v94
	v_mul_f32_e32 v90, 0x3fb8aa3b, v90
	v_mul_f32_e32 v95, 0x3fb8aa3b, v95
	v_mul_f32_e32 v96, 0x3fb8aa3b, v96
	v_mul_f32_e32 v97, 0x3fb8aa3b, v97
	v_mul_f32_e32 v91, 0x3fb8aa3b, v91
	v_mul_f32_e32 v92, 0x3fb8aa3b, v92
	v_exp_f32_e32 v94, v94
	v_exp_f32_e32 v90, v90
	v_exp_f32_e32 v95, v95
	v_exp_f32_e32 v96, v96
	v_exp_f32_e32 v97, v97
	v_exp_f32_e32 v91, v91
	v_exp_f32_e32 v92, v92
	v_mul_f32_e64 v93, v115, -v93
	v_mul_f32_e32 v93, 0x3fb8aa3b, v93
	v_exp_f32_e32 v142, v93
	v_add_f32_e32 v93, 1.0, v94
	v_add_f32_e32 v94, 1.0, v90
	v_add_f32_e32 v95, 1.0, v95
	v_add_f32_e32 v96, 1.0, v96
	v_add_f32_e32 v97, 1.0, v97
	v_add_f32_e32 v134, 1.0, v91
	v_add_f32_e32 v135, 1.0, v92
	v_rcp_f32_e32 v90, v93
	v_rcp_f32_e32 v92, v94
	v_rcp_f32_e32 v91, v95
	v_rcp_f32_e32 v94, v96
	v_rcp_f32_e32 v95, v97
	v_rcp_f32_e32 v93, v134
	v_rcp_f32_e32 v96, v135
	v_mul_f32_e64 v82, v115, -v82
	v_mul_f32_e64 v84, v115, -v84
	v_add_f32_e32 v97, 1.0, v142
	v_mul_f32_e32 v82, 0x3fb8aa3b, v82
	v_mul_f32_e32 v84, 0x3fb8aa3b, v84
	v_rcp_f32_e32 v97, v97
	v_mul_f32_e64 v86, v115, -v86
	v_mul_f32_e64 v88, v115, -v88
	v_mul_f32_e32 v86, 0x3fb8aa3b, v86
	v_mul_f32_e32 v88, 0x3fb8aa3b, v88
	v_exp_f32_e32 v86, v86
	v_mul_f32_e64 v83, v115, -v83
	v_exp_f32_e32 v88, v88
	v_mul_f32_e64 v85, v115, -v85
	v_mul_f32_e32 v83, 0x3fb8aa3b, v83
	v_mul_f32_e32 v85, 0x3fb8aa3b, v85
	v_add_f32_e32 v86, 1.0, v86
	v_add_f32_e32 v88, 1.0, v88
	s_waitcnt vmcnt(7)
	v_lshlrev_b32_e32 v134, 16, v118
	v_and_b32_e32 v135, 0xffff0000, v118
	v_lshlrev_b32_e32 v118, 16, v119
	v_and_b32_e32 v119, 0xffff0000, v119
	s_waitcnt vmcnt(6)
	v_lshlrev_b32_e32 v138, 16, v122
	v_and_b32_e32 v139, 0xffff0000, v122
	v_lshlrev_b32_e32 v122, 16, v123
	v_and_b32_e32 v123, 0xffff0000, v123
	v_pk_fma_f32 v[94:95], v[94:95], v[122:123], v[118:119]
	v_pk_fma_f32 v[90:91], v[90:91], v[138:139], v[134:135]
	v_mul_f32_e32 v119, v95, v95
	v_mul_f32_e32 v118, v91, v91
	v_fmac_f32_e32 v118, v90, v90
	v_fmac_f32_e32 v119, v94, v94
	v_cvt_pk_bf16_f32 v90, v90, v91
	v_cvt_pk_bf16_f32 v91, v94, v95
	v_exp_f32_e32 v122, v82
	v_mul_f32_e64 v82, v115, -v87
	s_waitcnt vmcnt(3)
	v_lshlrev_b32_e32 v94, 16, v126
	v_and_b32_e32 v95, 0xffff0000, v126
	v_exp_f32_e32 v126, v84
	v_mul_f32_e64 v84, v115, -v89
	v_mul_f32_e32 v82, 0x3fb8aa3b, v82
	v_mul_f32_e32 v84, 0x3fb8aa3b, v84
	v_exp_f32_e32 v87, v82
	v_exp_f32_e32 v89, v84
	v_lshlrev_b32_e32 v136, 16, v120
	v_and_b32_e32 v137, 0xffff0000, v120
	v_lshlrev_b32_e32 v120, 16, v121
	v_and_b32_e32 v121, 0xffff0000, v121
	v_lshlrev_b32_e32 v140, 16, v124
	v_and_b32_e32 v141, 0xffff0000, v124
	v_lshlrev_b32_e32 v124, 16, v125
	v_and_b32_e32 v125, 0xffff0000, v125
	v_pk_fma_f32 v[96:97], v[96:97], v[124:125], v[120:121]
	v_exp_f32_e32 v124, v83
	v_exp_f32_e32 v115, v85
	v_add_f32_e32 v87, 1.0, v87
	v_add_f32_e32 v89, 1.0, v89
	v_rcp_f32_e32 v82, v86
	v_rcp_f32_e32 v83, v87
	v_rcp_f32_e32 v84, v88
	v_rcp_f32_e32 v85, v89
	v_pk_fma_f32 v[92:93], v[92:93], v[140:141], v[136:137]
	v_add_f32_e32 v86, 1.0, v122
	v_add_f32_e32 v87, 1.0, v124
	v_add_f32_e32 v88, 1.0, v126
	v_add_f32_e32 v89, 1.0, v115
	v_add_f32_e32 v118, v118, v119
	v_mul_f32_e32 v119, v93, v93
	v_mul_f32_e32 v120, v97, v97
	v_rcp_f32_e32 v86, v86
	v_rcp_f32_e32 v87, v87
	v_rcp_f32_e32 v88, v88
	v_rcp_f32_e32 v89, v89
	v_fmac_f32_e32 v119, v92, v92
	v_fmac_f32_e32 v120, v96, v96
	v_cvt_pk_bf16_f32 v92, v92, v93
	v_cvt_pk_bf16_f32 v93, v96, v97
	v_lshlrev_b32_e32 v96, 16, v127
	v_and_b32_e32 v97, 0xffff0000, v127
	s_waitcnt vmcnt(2)
	v_lshlrev_b32_e32 v122, 16, v130
	v_and_b32_e32 v123, 0xffff0000, v130
	v_lshlrev_b32_e32 v126, 16, v131
	v_and_b32_e32 v127, 0xffff0000, v131
	v_add_f32_e32 v119, v119, v120
	v_pk_fma_f32 v[96:97], v[84:85], v[126:127], v[96:97]
	v_pk_fma_f32 v[82:83], v[82:83], v[122:123], v[94:95]
	v_add_f32_e32 v134, v118, v119
	v_lshlrev_b32_e32 v118, 16, v128
	v_and_b32_e32 v119, 0xffff0000, v128
	v_lshlrev_b32_e32 v120, 16, v129
	v_and_b32_e32 v121, 0xffff0000, v129
	v_lshlrev_b32_e32 v124, 16, v132
	v_and_b32_e32 v125, 0xffff0000, v132
	v_lshlrev_b32_e32 v128, 16, v133
	v_and_b32_e32 v129, 0xffff0000, v133
	v_mul_f32_e32 v84, v83, v83
	v_mul_f32_e32 v85, v97, v97
	v_pk_fma_f32 v[88:89], v[88:89], v[128:129], v[120:121]
	v_pk_fma_f32 v[86:87], v[86:87], v[124:125], v[118:119]
	v_fmac_f32_e32 v84, v82, v82
	v_fmac_f32_e32 v85, v96, v96
	v_add_f32_e32 v84, v84, v85
	v_mul_f32_e32 v85, v87, v87
	v_mul_f32_e32 v94, v89, v89
	v_fmac_f32_e32 v85, v86, v86
	v_fmac_f32_e32 v94, v88, v88
	v_add_f32_e32 v85, v85, v94
	v_add_f32_e32 v84, v84, v85
	v_add_f32_e32 v115, v134, v84
	ds_bpermute_b32 v118, v213, v115
	v_lshlrev_b64 v[116:117], 11, v[192:193]
	v_lshl_add_u64 v[84:85], s[52:53], 0, v[116:117]
	v_lshl_add_u64 v[94:95], v[160:161], 1, v[84:85]
	global_store_dwordx4 v[94:95], v[90:93], off sc1
	v_cvt_pk_bf16_f32 v84, v82, v83
	s_waitcnt lgkmcnt(0)
	v_add_f32_e32 v82, v115, v118
	ds_bpermute_b32 v83, v212, v82
	v_cmp_gt_f32_e32 vcc, s31, v114
	v_cvt_pk_bf16_f32 v85, v96, v97
	v_cvt_pk_bf16_f32 v86, v86, v87
	v_cvt_pk_bf16_f32 v87, v88, v89
	global_store_dwordx4 v[94:95], v[84:87], off offset:256 sc1
	s_and_saveexec_b64 s[44:45], s[40:41]
	s_cbranch_execz .LBB0_1773
; __device__ __forceinline__ float bf_lo(unsigned w) { return __uint_as_float(w << 16); }
; __device__ __forceinline__ float bf_hi(unsigned w) { return __uint_as_float(w & 0xffff0000u); }
; __device__ __forceinline__ float dot4(f32x4 a) { return (a[0] * a[0] + a[1] * a[1]) + (a[2] * a[2] + a[3] * a[3]); }
; __device__ __forceinline__ float fq_sum(float s) { s += __shfl_xor(s, 16); s += __shfl_xor(s, 32); return s; }
;     __device__ __forceinline__ void operator()(const f32x4 (&acc)[2][2][4][2], const Unit& u, int wr, int wc, int fr, int fq) const {
;     ...
;             for (int k = 0; k < NB; ++k) {
;                 const int ai = (g * NB + k) >> 2, m = (g * NB + k) & 3;
;                 const int row = u.pm * 256 + ai * 128 + wr * 64 + m * 16 + fr;
;                 float ss = 0.f;
; #pragma unroll
;                 for (int bj = 0; bj < 2; ++bj) {
;                     const size_t off = (size_t)row * 1024 + colb + bj * 128;
;                     const u32x4 w = xw[k][bj];
;                     const f32x4 x0 = (f32x4){bf_lo(w.x), bf_hi(w.x), bf_lo(w.y), bf_hi(w.y)}, x1 = (f32x4){bf_lo(w.z), bf_hi(w.z), bf_lo(w.w), bf_hi(w.w)};
;                     f32x4 d0 = acc[ai][bj][m][0], d1 = acc[ai][bj][m][1];
;                     if (MODE == 2) { const float r2 = rs8[ai][m] * rs8[ai][m]; d0 = d0 * r2; d1 = d1 * r2; }
;                     if (MODE == 1) {
;                         const float rs = rs8[ai][m];
;                         const u32x4 q = pw[k][bj];
;                         const f32x4 p0 = (f32x4){bf_lo(q.x), bf_hi(q.x), bf_lo(q.y), bf_hi(q.y)}, p1 = (f32x4){bf_lo(q.z), bf_hi(q.z), bf_lo(q.w), bf_hi(q.w)};
; #pragma unroll
;                         for (int i = 0; i < 4; ++i) { d0[i] = p0[i] * __builtin_amdgcn_rcpf(1.0f + __expf(-d0[i] * rs)); d1[i] = p1[i] * __builtin_amdgcn_rcpf(1.0f + __expf(-d1[i] * rs)); }
;                     }
;                     const f32x4 y0 = x0 + d0, y1 = x1 + d1;
;                     if (LAST) { *(f32x4*)(xout + off) = y0; *(f32x4*)(xout + off + 4) = y1; }
;                     else { ss += dot4(y0) + dot4(y1); *(u32x4*)(xb + off) = pack8(y0, y1); }
;                 }
;                 if (!LAST) { ss = fq_sum(ss); if (fq == 0) xs_out[(size_t)row * 16 + u.pn * 4 + wc] = ss; }
;             }
	v_lshl_add_u64 v[84:85], s[18:19], 0, v[190:191]
	v_lshl_add_u64 v[84:85], s[38:39], 2, v[84:85]
	s_lshl_b32 s48, s91, 2
	v_lshl_add_u64 v[84:85], v[84:85], 0, s[48:49]
	s_waitcnt lgkmcnt(0)
	v_add_f32_e32 v82, v82, v83
	global_store_dword v[84:85], v82, off
.LBB0_1773:
	s_or_b64 exec, exec, s[44:45]
	v_mul_f32_e32 v82, 0x4b800000, v114
	v_cndmask_b32_e32 v82, v114, v82, vcc
	v_rsq_f32_e32 v86, v82
	v_lshlrev_b32_e32 v84, 16, v110
	v_and_b32_e32 v85, 0xffff0000, v110
	v_and_b32_e32 v93, 0xffff0000, v106
	v_mul_f32_e32 v87, 0x45800000, v86
	v_cndmask_b32_e32 v110, v86, v87, vcc
	v_mul_f32_e64 v74, v110, -v74
	v_mul_f32_e32 v74, 0x3fb8aa3b, v74
	v_mul_f32_e64 v78, v110, -v78
	v_exp_f32_e32 v92, v74
	v_mul_f32_e64 v74, v110, -v79
	v_mul_f32_e32 v78, 0x3fb8aa3b, v78
	v_mul_f32_e32 v74, 0x3fb8aa3b, v74
	v_mul_f32_e64 v75, v110, -v75
	v_exp_f32_e32 v78, v78
	v_exp_f32_e32 v79, v74
	v_mul_f32_e32 v75, 0x3fb8aa3b, v75
	v_mul_f32_e64 v76, v110, -v76
	v_exp_f32_e32 v94, v75
	v_mul_f32_e32 v76, 0x3fb8aa3b, v76
	v_mul_f32_e64 v80, v110, -v80
	v_exp_f32_e32 v96, v76
	v_mul_f32_e64 v76, v110, -v81
	v_mul_f32_e32 v80, 0x3fb8aa3b, v80
	v_mul_f32_e32 v76, 0x3fb8aa3b, v76
	v_mul_f32_e64 v77, v110, -v77
	v_add_f32_e32 v78, 1.0, v78
	v_add_f32_e32 v79, 1.0, v79
	v_exp_f32_e32 v80, v80
	v_exp_f32_e32 v81, v76
	v_mul_f32_e32 v77, 0x3fb8aa3b, v77
	v_rcp_f32_e32 v74, v78
	v_add_f32_e32 v78, 1.0, v92
	v_rcp_f32_e32 v75, v79
	v_lshlrev_b32_e32 v92, 16, v106
	v_add_f32_e32 v79, 1.0, v94
	v_exp_f32_e32 v106, v77
	v_rcp_f32_e32 v78, v78
	v_rcp_f32_e32 v79, v79
	v_add_f32_e32 v80, 1.0, v80
	v_add_f32_e32 v81, 1.0, v81
	v_mul_f32_e64 v66, v110, -v66
	v_mul_f32_e64 v68, v110, -v68
	v_lshlrev_b32_e32 v88, 16, v112
	v_and_b32_e32 v89, 0xffff0000, v112
	v_lshlrev_b32_e32 v94, 16, v108
	v_and_b32_e32 v95, 0xffff0000, v108
	v_rcp_f32_e32 v76, v80
	v_add_f32_e32 v80, 1.0, v96
	v_rcp_f32_e32 v77, v81
	v_add_f32_e32 v81, 1.0, v106
	v_mul_f32_e32 v66, 0x3fb8aa3b, v66
	v_mul_f32_e32 v68, 0x3fb8aa3b, v68
	v_rcp_f32_e32 v80, v80
	v_rcp_f32_e32 v81, v81
	v_pk_fma_f32 v[74:75], v[74:75], v[92:93], v[84:85]
	v_pk_fma_f32 v[78:79], v[78:79], v[94:95], v[88:89]
	v_mul_f32_e64 v70, v110, -v70
	v_exp_f32_e32 v88, v66
	v_mul_f32_e64 v66, v110, -v71
	v_mul_f32_e64 v72, v110, -v72
	v_exp_f32_e32 v92, v68
	v_mul_f32_e64 v68, v110, -v73
	v_mul_f32_e32 v70, 0x3fb8aa3b, v70
	v_mul_f32_e32 v66, 0x3fb8aa3b, v66
	v_mul_f32_e32 v72, 0x3fb8aa3b, v72
	v_mul_f32_e32 v68, 0x3fb8aa3b, v68
	v_exp_f32_e32 v70, v70
	v_exp_f32_e32 v71, v66
	v_mul_f32_e64 v67, v110, -v67
	v_exp_f32_e32 v72, v72
	v_exp_f32_e32 v73, v68
	v_mul_f32_e64 v69, v110, -v69
	v_lshlrev_b32_e32 v90, 16, v113
	v_and_b32_e32 v91, 0xffff0000, v113
	v_lshlrev_b32_e32 v96, 16, v107
	v_and_b32_e32 v97, 0xffff0000, v107
	v_lshlrev_b32_e32 v106, 16, v109
	v_and_b32_e32 v107, 0xffff0000, v109
	v_mul_f32_e32 v67, 0x3fb8aa3b, v67
	v_mul_f32_e32 v69, 0x3fb8aa3b, v69
	v_pk_fma_f32 v[80:81], v[80:81], v[106:107], v[90:91]
	v_exp_f32_e32 v90, v67
	v_exp_f32_e32 v94, v69
	v_lshlrev_b32_e32 v86, 16, v111
	v_and_b32_e32 v87, 0xffff0000, v111
	v_pk_fma_f32 v[76:77], v[76:77], v[96:97], v[86:87]
	v_add_f32_e32 v70, 1.0, v70
	v_add_f32_e32 v71, 1.0, v71
	v_add_f32_e32 v72, 1.0, v72
	v_add_f32_e32 v73, 1.0, v73
	v_mul_f32_e32 v84, v75, v75
	v_mul_f32_e32 v85, v77, v77
	v_rcp_f32_e32 v66, v70
	v_rcp_f32_e32 v67, v71
	v_rcp_f32_e32 v68, v72
	v_rcp_f32_e32 v69, v73
	v_fmac_f32_e32 v84, v74, v74
	v_fmac_f32_e32 v85, v76, v76
	v_add_f32_e32 v70, 1.0, v88
	v_add_f32_e32 v71, 1.0, v90
	v_add_f32_e32 v72, 1.0, v92
	v_add_f32_e32 v73, 1.0, v94
	v_add_f32_e32 v84, v84, v85
	v_mul_f32_e32 v85, v79, v79
	v_mul_f32_e32 v86, v81, v81
	v_rcp_f32_e32 v70, v70
	v_rcp_f32_e32 v71, v71
	v_rcp_f32_e32 v72, v72
	v_rcp_f32_e32 v73, v73
	v_fmac_f32_e32 v85, v78, v78
	v_fmac_f32_e32 v86, v80, v80
	v_cvt_pk_bf16_f32 v74, v74, v75
	v_cvt_pk_bf16_f32 v75, v76, v77
	v_cvt_pk_bf16_f32 v76, v78, v79
	v_cvt_pk_bf16_f32 v77, v80, v81
	s_waitcnt vmcnt(3)
	v_lshlrev_b32_e32 v78, 16, v102
	v_and_b32_e32 v79, 0xffff0000, v102
	v_lshlrev_b32_e32 v80, 16, v103
	v_and_b32_e32 v81, 0xffff0000, v103
	s_waitcnt vmcnt(2)
	v_lshlrev_b32_e32 v88, 16, v98
	v_and_b32_e32 v89, 0xffff0000, v98
	v_lshlrev_b32_e32 v92, 16, v99
	v_and_b32_e32 v93, 0xffff0000, v99
	v_add_f32_e32 v85, v85, v86
	v_pk_fma_f32 v[80:81], v[68:69], v[92:93], v[80:81]
	v_pk_fma_f32 v[66:67], v[66:67], v[88:89], v[78:79]
	v_add_f32_e32 v96, v84, v85
	v_lshlrev_b32_e32 v84, 16, v104
	v_and_b32_e32 v85, 0xffff0000, v104
	v_lshlrev_b32_e32 v86, 16, v105
	v_and_b32_e32 v87, 0xffff0000, v105
	v_lshlrev_b32_e32 v90, 16, v100
	v_and_b32_e32 v91, 0xffff0000, v100
	v_lshlrev_b32_e32 v94, 16, v101
	v_and_b32_e32 v95, 0xffff0000, v101
	v_mul_f32_e32 v68, v67, v67
	v_mul_f32_e32 v69, v81, v81
	v_pk_fma_f32 v[72:73], v[72:73], v[94:95], v[86:87]
	v_pk_fma_f32 v[70:71], v[70:71], v[90:91], v[84:85]
	v_fmac_f32_e32 v68, v66, v66
	v_fmac_f32_e32 v69, v80, v80
	v_add_f32_e32 v68, v68, v69
	v_mul_f32_e32 v69, v71, v71
	v_mul_f32_e32 v78, v73, v73
	v_fmac_f32_e32 v69, v70, v70
	v_fmac_f32_e32 v78, v72, v72
	v_add_f32_e32 v69, v69, v78
	v_add_f32_e32 v68, v68, v69
	v_add_f32_e32 v84, v96, v68
	ds_bpermute_b32 v85, v213, v84
	s_waitcnt lgkmcnt(1)
	v_lshlrev_b64 v[82:83], 11, v[188:189]
	v_lshl_add_u64 v[68:69], s[52:53], 0, v[82:83]
	v_lshl_add_u64 v[78:79], v[160:161], 1, v[68:69]
	global_store_dwordx4 v[78:79], v[74:77], off sc1
	v_cvt_pk_bf16_f32 v68, v66, v67
	s_waitcnt lgkmcnt(0)
	v_add_f32_e32 v66, v84, v85
	ds_bpermute_b32 v67, v212, v66
	v_cvt_pk_bf16_f32 v69, v80, v81
	v_cvt_pk_bf16_f32 v70, v70, v71
	v_cvt_pk_bf16_f32 v71, v72, v73
	global_store_dwordx4 v[78:79], v[68:71], off offset:256 sc1
	s_and_saveexec_b64 s[44:45], s[40:41]
	s_cbranch_execz .LBB0_1775
	v_lshl_add_u64 v[68:69], s[18:19], 0, v[182:183]
	v_lshl_add_u64 v[68:69], s[38:39], 2, v[68:69]
	s_lshl_b32 s48, s91, 2
	v_lshl_add_u64 v[68:69], v[68:69], 0, s[48:49]
	s_waitcnt lgkmcnt(0)
	v_add_f32_e32 v66, v66, v67
	global_store_dword v[68:69], v66, off
;     __device__ __forceinline__ void operator()(const f32x4 (&acc)[2][2][4][2], const Unit& u, int wr, int wc, int fr, int fq) const {
;     ...
;         for (int g = 0; g < 8 / NB; ++g) {
;             u32x4 xw[NB][2], pw[NB][2];
; #pragma unroll
;             for (int k = 0; k < NB; ++k)
; #pragma unroll
;                 for (int bj = 0; bj < 2; ++bj) {
;                     const int ai = (g * NB + k) >> 2, m = (g * NB + k) & 3;
;                     const size_t off = (size_t)(u.pm * 256 + ai * 128 + wr * 64 + m * 16 + fr) * 1024 + colb + bj * 128;
;                     xw[k][bj] = *(const u32x4*)(xold + off);
;                     if (MODE == 1) pw[k][bj] = *(const u32x4*)(pg + off);
;                 }
; #pragma unroll
;             for (int k = 0; k < NB; ++k) {
;                 const int ai = (g * NB + k) >> 2, m = (g * NB + k) & 3;
;                 const int row = u.pm * 256 + ai * 128 + wr * 64 + m * 16 + fr;
;                 float ss = 0.f;
; #pragma unroll
;                 for (int bj = 0; bj < 2; ++bj) {
;                     const size_t off = (size_t)row * 1024 + colb + bj * 128;
;                     const u32x4 w = xw[k][bj];
;                     const f32x4 x0 = (f32x4){bf_lo(w.x), bf_hi(w.x), bf_lo(w.y), bf_hi(w.y)}, x1 = (f32x4){bf_lo(w.z), bf_hi(w.z), bf_lo(w.w), bf_hi(w.w)};
;                     f32x4 d0 = acc[ai][bj][m][0], d1 = acc[ai][bj][m][1];
;                     if (MODE == 2) { const float r2 = rs8[ai][m] * rs8[ai][m]; d0 = d0 * r2; d1 = d1 * r2; }
;                     if (MODE == 1) {
;                         const float rs = rs8[ai][m];
;                         const u32x4 q = pw[k][bj];
;                         const f32x4 p0 = (f32x4){bf_lo(q.x), bf_hi(q.x), bf_lo(q.y), bf_hi(q.y)}, p1 = (f32x4){bf_lo(q.z), bf_hi(q.z), bf_lo(q.w), bf_hi(q.w)};
; #pragma unroll
;                         for (int i = 0; i < 4; ++i) { d0[i] = p0[i] * __builtin_amdgcn_rcpf(1.0f + __expf(-d0[i] * rs)); d1[i] = p1[i] * __builtin_amdgcn_rcpf(1.0f + __expf(-d1[i] * rs)); }
;                     }
;                     const f32x4 y0 = x0 + d0, y1 = x1 + d1;
;                     if (LAST) { *(f32x4*)(xout + off) = y0; *(f32x4*)(xout + off + 4) = y1; }
;                     else { ss += dot4(y0) + dot4(y1); *(u32x4*)(xb + off) = pack8(y0, y1); }
;                 }
.LBB0_1775:
	s_or_b64 exec, exec, s[44:45]
	s_waitcnt lgkmcnt(0)
	v_lshlrev_b64 v[66:67], 10, v[180:181]
	v_lshl_add_u64 v[66:67], v[66:67], 0, v[160:161]
	v_lshlrev_b64 v[66:67], 1, v[66:67]
	v_lshl_add_u64 v[68:69], s[46:47], 0, v[66:67]
	global_load_dwordx4 v[86:89], v[68:69], off
	v_lshl_add_u64 v[68:69], s[50:51], 0, v[66:67]
	global_load_dwordx4 v[90:93], v[68:69], off
	v_pk_add_f32 v[68:69], v[184:185], v[186:187]
	v_lshlrev_b64 v[70:71], 10, v[176:177]
	v_pk_fma_f32 v[82:83], v[68:69], s[28:29], v[162:163] op_sel_hi:[1,0,0]
	v_lshl_add_u64 v[68:69], v[70:71], 0, v[160:161]
	v_mul_f32_e32 v70, 0x4b800000, v83
	v_lshlrev_b64 v[68:69], 1, v[68:69]
	v_cmp_gt_f32_e64 s[44:45], s31, v83
	v_or_b32_e32 v66, 0x100, v66
	v_lshl_add_u64 v[72:73], s[50:51], 0, v[68:69]
	v_cndmask_b32_e64 v74, v83, v70, s[44:45]
	v_lshl_add_u64 v[70:71], s[46:47], 0, v[68:69]
	v_or_b32_e32 v68, 0x100, v68
	v_rsq_f32_e32 v83, v74
	v_lshl_add_u64 v[94:95], s[46:47], 0, v[66:67]
	v_lshl_add_u64 v[66:67], s[50:51], 0, v[66:67]
	global_load_dwordx4 v[78:81], v[70:71], off
	global_load_dwordx4 v[74:77], v[72:73], off
	v_lshl_add_u64 v[70:71], s[46:47], 0, v[68:69]
	v_lshl_add_u64 v[68:69], s[50:51], 0, v[68:69]
	global_load_dwordx4 v[94:97], v[94:95], off
	s_nop 0
	global_load_dwordx4 v[98:101], v[66:67], off
	s_nop 0
	global_load_dwordx4 v[70:73], v[70:71], off
	s_nop 0
	global_load_dwordx4 v[66:69], v[68:69], off
	v_mul_f32_e32 v102, 0x45800000, v83
	v_cndmask_b32_e64 v83, v83, v102, s[44:45]
	v_mul_f32_e64 v62, v83, -v62
	v_mul_f32_e64 v58, v83, -v58
	v_mul_f32_e64 v63, v83, -v63
	v_mul_f32_e64 v64, v83, -v64
	v_mul_f32_e64 v65, v83, -v65
	v_mul_f32_e64 v59, v83, -v59
	v_mul_f32_e64 v60, v83, -v60
	v_mul_f32_e32 v62, 0x3fb8aa3b, v62
	v_mul_f32_e32 v58, 0x3fb8aa3b, v58
	v_mul_f32_e32 v63, 0x3fb8aa3b, v63
	v_mul_f32_e32 v64, 0x3fb8aa3b, v64
	v_mul_f32_e32 v65, 0x3fb8aa3b, v65
	v_mul_f32_e32 v59, 0x3fb8aa3b, v59
	v_mul_f32_e32 v60, 0x3fb8aa3b, v60
	v_exp_f32_e32 v62, v62
	v_exp_f32_e32 v58, v58
	v_exp_f32_e32 v63, v63
	v_exp_f32_e32 v64, v64
	v_exp_f32_e32 v65, v65
	v_exp_f32_e32 v59, v59
	v_exp_f32_e32 v60, v60
	v_mul_f32_e64 v61, v83, -v61
	v_mul_f32_e32 v61, 0x3fb8aa3b, v61
	v_exp_f32_e32 v110, v61
	v_add_f32_e32 v61, 1.0, v62
	v_add_f32_e32 v62, 1.0, v58
	v_add_f32_e32 v63, 1.0, v63
	v_add_f32_e32 v64, 1.0, v64
	v_add_f32_e32 v65, 1.0, v65
	v_add_f32_e32 v102, 1.0, v59
	v_add_f32_e32 v103, 1.0, v60
	v_rcp_f32_e32 v58, v61
	v_rcp_f32_e32 v60, v62
	v_rcp_f32_e32 v59, v63
	v_rcp_f32_e32 v62, v64
	v_rcp_f32_e32 v63, v65
	v_rcp_f32_e32 v61, v102
	v_rcp_f32_e32 v64, v103
	v_mul_f32_e64 v50, v83, -v50
	v_mul_f32_e64 v52, v83, -v52
	v_add_f32_e32 v65, 1.0, v110
	v_mul_f32_e32 v50, 0x3fb8aa3b, v50
	v_mul_f32_e32 v52, 0x3fb8aa3b, v52
	v_rcp_f32_e32 v65, v65
	v_mul_f32_e64 v54, v83, -v54
	v_mul_f32_e64 v56, v83, -v56
	v_mul_f32_e32 v54, 0x3fb8aa3b, v54
	v_mul_f32_e32 v56, 0x3fb8aa3b, v56
	v_exp_f32_e32 v54, v54
	v_mul_f32_e64 v51, v83, -v51
	v_exp_f32_e32 v56, v56
	v_mul_f32_e64 v53, v83, -v53
	v_mul_f32_e32 v51, 0x3fb8aa3b, v51
	v_mul_f32_e32 v53, 0x3fb8aa3b, v53
	v_add_f32_e32 v54, 1.0, v54
	v_add_f32_e32 v56, 1.0, v56
	s_waitcnt vmcnt(7)
	v_lshlrev_b32_e32 v102, 16, v86
	v_and_b32_e32 v103, 0xffff0000, v86
	v_lshlrev_b32_e32 v86, 16, v87
	v_and_b32_e32 v87, 0xffff0000, v87
	s_waitcnt vmcnt(6)
	v_lshlrev_b32_e32 v106, 16, v90
	v_and_b32_e32 v107, 0xffff0000, v90
	v_lshlrev_b32_e32 v90, 16, v91
	v_and_b32_e32 v91, 0xffff0000, v91
	v_pk_fma_f32 v[62:63], v[62:63], v[90:91], v[86:87]
	v_pk_fma_f32 v[58:59], v[58:59], v[106:107], v[102:103]
	v_mul_f32_e32 v87, v63, v63
	v_mul_f32_e32 v86, v59, v59
	v_fmac_f32_e32 v86, v58, v58
	v_fmac_f32_e32 v87, v62, v62
	v_cvt_pk_bf16_f32 v58, v58, v59
	v_cvt_pk_bf16_f32 v59, v62, v63
	v_exp_f32_e32 v90, v50
	v_mul_f32_e64 v50, v83, -v55
	s_waitcnt vmcnt(3)
	v_lshlrev_b32_e32 v62, 16, v94
	v_and_b32_e32 v63, 0xffff0000, v94
	v_exp_f32_e32 v94, v52
	v_mul_f32_e64 v52, v83, -v57
	v_mul_f32_e32 v50, 0x3fb8aa3b, v50
	v_mul_f32_e32 v52, 0x3fb8aa3b, v52
	v_exp_f32_e32 v55, v50
	v_exp_f32_e32 v57, v52
	v_lshlrev_b32_e32 v104, 16, v88
	v_and_b32_e32 v105, 0xffff0000, v88
	v_lshlrev_b32_e32 v88, 16, v89
	v_and_b32_e32 v89, 0xffff0000, v89
	v_lshlrev_b32_e32 v108, 16, v92
	v_and_b32_e32 v109, 0xffff0000, v92
	v_lshlrev_b32_e32 v92, 16, v93
	v_and_b32_e32 v93, 0xffff0000, v93
	v_pk_fma_f32 v[64:65], v[64:65], v[92:93], v[88:89]
	v_exp_f32_e32 v92, v51
	v_exp_f32_e32 v83, v53
	v_add_f32_e32 v55, 1.0, v55
	v_add_f32_e32 v57, 1.0, v57
	v_rcp_f32_e32 v50, v54
	v_rcp_f32_e32 v51, v55
	v_rcp_f32_e32 v52, v56
	v_rcp_f32_e32 v53, v57
	v_pk_fma_f32 v[60:61], v[60:61], v[108:109], v[104:105]
	v_add_f32_e32 v54, 1.0, v90
	v_add_f32_e32 v55, 1.0, v92
	v_add_f32_e32 v56, 1.0, v94
	v_add_f32_e32 v57, 1.0, v83
	v_add_f32_e32 v86, v86, v87
	v_mul_f32_e32 v87, v61, v61
	v_mul_f32_e32 v88, v65, v65
	v_rcp_f32_e32 v54, v54
	v_rcp_f32_e32 v55, v55
	v_rcp_f32_e32 v56, v56
	v_rcp_f32_e32 v57, v57
	v_fmac_f32_e32 v87, v60, v60
	v_fmac_f32_e32 v88, v64, v64
	v_cvt_pk_bf16_f32 v60, v60, v61
	v_cvt_pk_bf16_f32 v61, v64, v65
	v_lshlrev_b32_e32 v64, 16, v95
	v_and_b32_e32 v65, 0xffff0000, v95
	s_waitcnt vmcnt(2)
	v_lshlrev_b32_e32 v90, 16, v98
	v_and_b32_e32 v91, 0xffff0000, v98
	v_lshlrev_b32_e32 v94, 16, v99
	v_and_b32_e32 v95, 0xffff0000, v99
	v_add_f32_e32 v87, v87, v88
	v_pk_fma_f32 v[64:65], v[52:53], v[94:95], v[64:65]
	v_pk_fma_f32 v[50:51], v[50:51], v[90:91], v[62:63]
	v_add_f32_e32 v102, v86, v87
	v_lshlrev_b32_e32 v86, 16, v96
	v_and_b32_e32 v87, 0xffff0000, v96
	v_lshlrev_b32_e32 v88, 16, v97
	v_and_b32_e32 v89, 0xffff0000, v97
	v_lshlrev_b32_e32 v92, 16, v100
	v_and_b32_e32 v93, 0xffff0000, v100
	v_lshlrev_b32_e32 v96, 16, v101
	v_and_b32_e32 v97, 0xffff0000, v101
	v_mul_f32_e32 v52, v51, v51
	v_mul_f32_e32 v53, v65, v65
	v_pk_fma_f32 v[56:57], v[56:57], v[96:97], v[88:89]
	v_pk_fma_f32 v[54:55], v[54:55], v[92:93], v[86:87]
	v_fmac_f32_e32 v52, v50, v50
	v_fmac_f32_e32 v53, v64, v64
	v_add_f32_e32 v52, v52, v53
	v_mul_f32_e32 v53, v55, v55
	v_mul_f32_e32 v62, v57, v57
	v_fmac_f32_e32 v53, v54, v54
	v_fmac_f32_e32 v62, v56, v56
	v_add_f32_e32 v53, v53, v62
	v_add_f32_e32 v52, v52, v53
	v_add_f32_e32 v83, v102, v52
	ds_bpermute_b32 v86, v213, v83
	v_lshlrev_b64 v[84:85], 11, v[180:181]
	v_lshl_add_u64 v[52:53], s[52:53], 0, v[84:85]
	v_lshl_add_u64 v[62:63], v[160:161], 1, v[52:53]
	global_store_dwordx4 v[62:63], v[58:61], off sc1
	v_cvt_pk_bf16_f32 v52, v50, v51
	s_waitcnt lgkmcnt(0)
	v_add_f32_e32 v50, v83, v86
	ds_bpermute_b32 v51, v212, v50
	v_cmp_gt_f32_e32 vcc, s31, v82
	v_cvt_pk_bf16_f32 v53, v64, v65
	v_cvt_pk_bf16_f32 v54, v54, v55
	v_cvt_pk_bf16_f32 v55, v56, v57
	global_store_dwordx4 v[62:63], v[52:55], off offset:256 sc1
	s_and_saveexec_b64 s[44:45], s[40:41]
	s_cbranch_execz .LBB0_1777
; __device__ __forceinline__ float bf_lo(unsigned w) { return __uint_as_float(w << 16); }
; __device__ __forceinline__ float bf_hi(unsigned w) { return __uint_as_float(w & 0xffff0000u); }
; __device__ __forceinline__ float dot4(f32x4 a) { return (a[0] * a[0] + a[1] * a[1]) + (a[2] * a[2] + a[3] * a[3]); }
; __device__ __forceinline__ float fq_sum(float s) { s += __shfl_xor(s, 16); s += __shfl_xor(s, 32); return s; }
;     __device__ __forceinline__ void operator()(const f32x4 (&acc)[2][2][4][2], const Unit& u, int wr, int wc, int fr, int fq) const {
;     ...
;             for (int k = 0; k < NB; ++k) {
;                 const int ai = (g * NB + k) >> 2, m = (g * NB + k) & 3;
;                 const int row = u.pm * 256 + ai * 128 + wr * 64 + m * 16 + fr;
;                 float ss = 0.f;
; #pragma unroll
;                 for (int bj = 0; bj < 2; ++bj) {
;                     const size_t off = (size_t)row * 1024 + colb + bj * 128;
;                     const u32x4 w = xw[k][bj];
;                     const f32x4 x0 = (f32x4){bf_lo(w.x), bf_hi(w.x), bf_lo(w.y), bf_hi(w.y)}, x1 = (f32x4){bf_lo(w.z), bf_hi(w.z), bf_lo(w.w), bf_hi(w.w)};
;                     f32x4 d0 = acc[ai][bj][m][0], d1 = acc[ai][bj][m][1];
;                     if (MODE == 2) { const float r2 = rs8[ai][m] * rs8[ai][m]; d0 = d0 * r2; d1 = d1 * r2; }
;                     if (MODE == 1) {
;                         const float rs = rs8[ai][m];
;                         const u32x4 q = pw[k][bj];
;                         const f32x4 p0 = (f32x4){bf_lo(q.x), bf_hi(q.x), bf_lo(q.y), bf_hi(q.y)}, p1 = (f32x4){bf_lo(q.z), bf_hi(q.z), bf_lo(q.w), bf_hi(q.w)};
; #pragma unroll
;                         for (int i = 0; i < 4; ++i) { d0[i] = p0[i] * __builtin_amdgcn_rcpf(1.0f + __expf(-d0[i] * rs)); d1[i] = p1[i] * __builtin_amdgcn_rcpf(1.0f + __expf(-d1[i] * rs)); }
;                     }
;                     const f32x4 y0 = x0 + d0, y1 = x1 + d1;
;                     if (LAST) { *(f32x4*)(xout + off) = y0; *(f32x4*)(xout + off + 4) = y1; }
;                     else { ss += dot4(y0) + dot4(y1); *(u32x4*)(xb + off) = pack8(y0, y1); }
;                 }
;                 if (!LAST) { ss = fq_sum(ss); if (fq == 0) xs_out[(size_t)row * 16 + u.pn * 4 + wc] = ss; }
;             }
	v_lshl_add_u64 v[52:53], s[18:19], 0, v[178:179]
	v_lshl_add_u64 v[52:53], s[38:39], 2, v[52:53]
	s_lshl_b32 s48, s91, 2
	v_lshl_add_u64 v[52:53], v[52:53], 0, s[48:49]
	s_waitcnt lgkmcnt(0)
	v_add_f32_e32 v50, v50, v51
	global_store_dword v[52:53], v50, off
.LBB0_1777:
	s_or_b64 exec, exec, s[44:45]
	v_mul_f32_e32 v50, 0x4b800000, v82
	v_cndmask_b32_e32 v50, v82, v50, vcc
	v_rsq_f32_e32 v54, v50
	v_lshlrev_b32_e32 v52, 16, v78
	v_and_b32_e32 v53, 0xffff0000, v78
	v_and_b32_e32 v61, 0xffff0000, v74
	v_mul_f32_e32 v55, 0x45800000, v54
	v_cndmask_b32_e32 v78, v54, v55, vcc
	v_mul_f32_e64 v42, v78, -v42
	v_mul_f32_e32 v42, 0x3fb8aa3b, v42
	v_mul_f32_e64 v46, v78, -v46
	v_exp_f32_e32 v60, v42
	v_mul_f32_e64 v42, v78, -v47
	v_mul_f32_e32 v46, 0x3fb8aa3b, v46
	v_mul_f32_e32 v42, 0x3fb8aa3b, v42
	v_mul_f32_e64 v43, v78, -v43
	v_exp_f32_e32 v46, v46
	v_exp_f32_e32 v47, v42
	v_mul_f32_e32 v43, 0x3fb8aa3b, v43
	v_mul_f32_e64 v44, v78, -v44
	v_exp_f32_e32 v62, v43
	v_mul_f32_e32 v44, 0x3fb8aa3b, v44
	v_mul_f32_e64 v48, v78, -v48
	v_exp_f32_e32 v64, v44
	v_mul_f32_e64 v44, v78, -v49
	v_mul_f32_e32 v48, 0x3fb8aa3b, v48
	v_mul_f32_e32 v44, 0x3fb8aa3b, v44
	v_mul_f32_e64 v45, v78, -v45
	v_add_f32_e32 v46, 1.0, v46
	v_add_f32_e32 v47, 1.0, v47
	v_exp_f32_e32 v48, v48
	v_exp_f32_e32 v49, v44
	v_mul_f32_e32 v45, 0x3fb8aa3b, v45
	v_rcp_f32_e32 v42, v46
	v_add_f32_e32 v46, 1.0, v60
	v_rcp_f32_e32 v43, v47
	v_lshlrev_b32_e32 v60, 16, v74
	v_add_f32_e32 v47, 1.0, v62
	v_exp_f32_e32 v74, v45
	v_rcp_f32_e32 v46, v46
	v_rcp_f32_e32 v47, v47
	v_add_f32_e32 v48, 1.0, v48
	v_add_f32_e32 v49, 1.0, v49
	v_mul_f32_e64 v34, v78, -v34
	v_mul_f32_e64 v36, v78, -v36
	v_lshlrev_b32_e32 v56, 16, v80
	v_and_b32_e32 v57, 0xffff0000, v80
	v_lshlrev_b32_e32 v62, 16, v76
	v_and_b32_e32 v63, 0xffff0000, v76
	v_rcp_f32_e32 v44, v48
	v_add_f32_e32 v48, 1.0, v64
	v_rcp_f32_e32 v45, v49
	v_add_f32_e32 v49, 1.0, v74
	v_mul_f32_e32 v34, 0x3fb8aa3b, v34
	v_mul_f32_e32 v36, 0x3fb8aa3b, v36
	v_rcp_f32_e32 v48, v48
	v_rcp_f32_e32 v49, v49
	v_pk_fma_f32 v[42:43], v[42:43], v[60:61], v[52:53]
	v_pk_fma_f32 v[46:47], v[46:47], v[62:63], v[56:57]
	v_mul_f32_e64 v38, v78, -v38
	v_exp_f32_e32 v56, v34
	v_mul_f32_e64 v34, v78, -v39
	v_mul_f32_e64 v40, v78, -v40
	v_exp_f32_e32 v60, v36
	v_mul_f32_e64 v36, v78, -v41
	v_mul_f32_e32 v38, 0x3fb8aa3b, v38
	v_mul_f32_e32 v34, 0x3fb8aa3b, v34
	v_mul_f32_e32 v40, 0x3fb8aa3b, v40
	v_mul_f32_e32 v36, 0x3fb8aa3b, v36
	v_exp_f32_e32 v38, v38
	v_exp_f32_e32 v39, v34
	v_mul_f32_e64 v35, v78, -v35
	v_exp_f32_e32 v40, v40
	v_exp_f32_e32 v41, v36
	v_mul_f32_e64 v37, v78, -v37
	v_lshlrev_b32_e32 v58, 16, v81
	v_and_b32_e32 v59, 0xffff0000, v81
	v_lshlrev_b32_e32 v64, 16, v75
	v_and_b32_e32 v65, 0xffff0000, v75
	v_lshlrev_b32_e32 v74, 16, v77
	v_and_b32_e32 v75, 0xffff0000, v77
	v_mul_f32_e32 v35, 0x3fb8aa3b, v35
	v_mul_f32_e32 v37, 0x3fb8aa3b, v37
	v_pk_fma_f32 v[48:49], v[48:49], v[74:75], v[58:59]
	v_exp_f32_e32 v58, v35
	v_exp_f32_e32 v62, v37
	v_lshlrev_b32_e32 v54, 16, v79
	v_and_b32_e32 v55, 0xffff0000, v79
	v_pk_fma_f32 v[44:45], v[44:45], v[64:65], v[54:55]
	v_add_f32_e32 v38, 1.0, v38
	v_add_f32_e32 v39, 1.0, v39
	v_add_f32_e32 v40, 1.0, v40
	v_add_f32_e32 v41, 1.0, v41
	v_mul_f32_e32 v52, v43, v43
	v_mul_f32_e32 v53, v45, v45
	v_rcp_f32_e32 v34, v38
	v_rcp_f32_e32 v35, v39
	v_rcp_f32_e32 v36, v40
	v_rcp_f32_e32 v37, v41
	v_fmac_f32_e32 v52, v42, v42
	v_fmac_f32_e32 v53, v44, v44
	v_add_f32_e32 v38, 1.0, v56
	v_add_f32_e32 v39, 1.0, v58
	v_add_f32_e32 v40, 1.0, v60
	v_add_f32_e32 v41, 1.0, v62
	v_add_f32_e32 v52, v52, v53
	v_mul_f32_e32 v53, v47, v47
	v_mul_f32_e32 v54, v49, v49
	v_rcp_f32_e32 v38, v38
	v_rcp_f32_e32 v39, v39
	v_rcp_f32_e32 v40, v40
	v_rcp_f32_e32 v41, v41
	v_fmac_f32_e32 v53, v46, v46
	v_fmac_f32_e32 v54, v48, v48
	v_cvt_pk_bf16_f32 v42, v42, v43
	v_cvt_pk_bf16_f32 v43, v44, v45
	v_cvt_pk_bf16_f32 v44, v46, v47
	v_cvt_pk_bf16_f32 v45, v48, v49
	s_waitcnt vmcnt(3)
	v_lshlrev_b32_e32 v46, 16, v70
	v_and_b32_e32 v47, 0xffff0000, v70
	v_lshlrev_b32_e32 v48, 16, v71
	v_and_b32_e32 v49, 0xffff0000, v71
	s_waitcnt vmcnt(2)
	v_lshlrev_b32_e32 v56, 16, v66
	v_and_b32_e32 v57, 0xffff0000, v66
	v_lshlrev_b32_e32 v60, 16, v67
	v_and_b32_e32 v61, 0xffff0000, v67
	v_add_f32_e32 v53, v53, v54
	v_pk_fma_f32 v[48:49], v[36:37], v[60:61], v[48:49]
	v_pk_fma_f32 v[34:35], v[34:35], v[56:57], v[46:47]
	v_add_f32_e32 v64, v52, v53
	v_lshlrev_b32_e32 v52, 16, v72
	v_and_b32_e32 v53, 0xffff0000, v72
	v_lshlrev_b32_e32 v54, 16, v73
	v_and_b32_e32 v55, 0xffff0000, v73
	v_lshlrev_b32_e32 v58, 16, v68
	v_and_b32_e32 v59, 0xffff0000, v68
	v_lshlrev_b32_e32 v62, 16, v69
	v_and_b32_e32 v63, 0xffff0000, v69
	v_mul_f32_e32 v36, v35, v35
	v_mul_f32_e32 v37, v49, v49
	v_pk_fma_f32 v[40:41], v[40:41], v[62:63], v[54:55]
	v_pk_fma_f32 v[38:39], v[38:39], v[58:59], v[52:53]
	v_fmac_f32_e32 v36, v34, v34
	v_fmac_f32_e32 v37, v48, v48
	v_add_f32_e32 v36, v36, v37
	v_mul_f32_e32 v37, v39, v39
	v_mul_f32_e32 v46, v41, v41
	v_fmac_f32_e32 v37, v38, v38
	v_fmac_f32_e32 v46, v40, v40
	v_add_f32_e32 v37, v37, v46
	v_add_f32_e32 v36, v36, v37
	v_add_f32_e32 v52, v64, v36
	ds_bpermute_b32 v53, v213, v52
	s_waitcnt lgkmcnt(1)
	v_lshlrev_b64 v[50:51], 11, v[176:177]
	v_lshl_add_u64 v[36:37], s[52:53], 0, v[50:51]
	v_lshl_add_u64 v[46:47], v[160:161], 1, v[36:37]
	global_store_dwordx4 v[46:47], v[42:45], off sc1
	v_cvt_pk_bf16_f32 v36, v34, v35
	s_waitcnt lgkmcnt(0)
	v_add_f32_e32 v34, v52, v53
	ds_bpermute_b32 v35, v212, v34
	v_cvt_pk_bf16_f32 v37, v48, v49
	v_cvt_pk_bf16_f32 v38, v38, v39
	v_cvt_pk_bf16_f32 v39, v40, v41
	global_store_dwordx4 v[46:47], v[36:39], off offset:256 sc1
	s_and_saveexec_b64 s[44:45], s[40:41]
	s_cbranch_execz .LBB0_1779
	v_lshl_add_u64 v[36:37], s[18:19], 0, v[170:171]
	v_lshl_add_u64 v[36:37], s[38:39], 2, v[36:37]
	s_lshl_b32 s48, s91, 2
	v_lshl_add_u64 v[36:37], v[36:37], 0, s[48:49]
	s_waitcnt lgkmcnt(0)
	v_add_f32_e32 v34, v34, v35
	global_store_dword v[36:37], v34, off
;     __device__ __forceinline__ void operator()(const f32x4 (&acc)[2][2][4][2], const Unit& u, int wr, int wc, int fr, int fq) const {
;     ...
;         for (int g = 0; g < 8 / NB; ++g) {
;             u32x4 xw[NB][2], pw[NB][2];
; #pragma unroll
;             for (int k = 0; k < NB; ++k)
; #pragma unroll
;                 for (int bj = 0; bj < 2; ++bj) {
;                     const int ai = (g * NB + k) >> 2, m = (g * NB + k) & 3;
;                     const size_t off = (size_t)(u.pm * 256 + ai * 128 + wr * 64 + m * 16 + fr) * 1024 + colb + bj * 128;
;                     xw[k][bj] = *(const u32x4*)(xold + off);
;                     if (MODE == 1) pw[k][bj] = *(const u32x4*)(pg + off);
;                 }
; #pragma unroll
;             for (int k = 0; k < NB; ++k) {
;                 const int ai = (g * NB + k) >> 2, m = (g * NB + k) & 3;
;                 const int row = u.pm * 256 + ai * 128 + wr * 64 + m * 16 + fr;
;                 float ss = 0.f;
; #pragma unroll
;                 for (int bj = 0; bj < 2; ++bj) {
;                     const size_t off = (size_t)row * 1024 + colb + bj * 128;
;                     const u32x4 w = xw[k][bj];
;                     const f32x4 x0 = (f32x4){bf_lo(w.x), bf_hi(w.x), bf_lo(w.y), bf_hi(w.y)}, x1 = (f32x4){bf_lo(w.z), bf_hi(w.z), bf_lo(w.w), bf_hi(w.w)};
;                     f32x4 d0 = acc[ai][bj][m][0], d1 = acc[ai][bj][m][1];
;                     if (MODE == 2) { const float r2 = rs8[ai][m] * rs8[ai][m]; d0 = d0 * r2; d1 = d1 * r2; }
;                     if (MODE == 1) {
;                         const float rs = rs8[ai][m];
;                         const u32x4 q = pw[k][bj];
;                         const f32x4 p0 = (f32x4){bf_lo(q.x), bf_hi(q.x), bf_lo(q.y), bf_hi(q.y)}, p1 = (f32x4){bf_lo(q.z), bf_hi(q.z), bf_lo(q.w), bf_hi(q.w)};
; #pragma unroll
;                         for (int i = 0; i < 4; ++i) { d0[i] = p0[i] * __builtin_amdgcn_rcpf(1.0f + __expf(-d0[i] * rs)); d1[i] = p1[i] * __builtin_amdgcn_rcpf(1.0f + __expf(-d1[i] * rs)); }
;                     }
;                     const f32x4 y0 = x0 + d0, y1 = x1 + d1;
;                     if (LAST) { *(f32x4*)(xout + off) = y0; *(f32x4*)(xout + off + 4) = y1; }
;                     else { ss += dot4(y0) + dot4(y1); *(u32x4*)(xb + off) = pack8(y0, y1); }
;                 }
.LBB0_1779:
	s_or_b64 exec, exec, s[44:45]
	s_waitcnt lgkmcnt(0)
	v_lshlrev_b64 v[34:35], 10, v[168:169]
	v_lshl_add_u64 v[34:35], v[34:35], 0, v[160:161]
	v_lshlrev_b64 v[34:35], 1, v[34:35]
	v_lshl_add_u64 v[36:37], s[46:47], 0, v[34:35]
	global_load_dwordx4 v[54:57], v[36:37], off
	v_lshl_add_u64 v[36:37], s[50:51], 0, v[34:35]
	global_load_dwordx4 v[58:61], v[36:37], off
	v_pk_add_f32 v[36:37], v[172:173], v[174:175]
	v_lshlrev_b64 v[38:39], 10, v[164:165]
	v_pk_fma_f32 v[50:51], v[36:37], s[28:29], v[162:163] op_sel_hi:[1,0,0]
	v_lshl_add_u64 v[36:37], v[38:39], 0, v[160:161]
	v_mul_f32_e32 v38, 0x4b800000, v51
	v_lshlrev_b64 v[36:37], 1, v[36:37]
	v_cmp_gt_f32_e64 s[44:45], s31, v51
	v_or_b32_e32 v34, 0x100, v34
	v_lshl_add_u64 v[40:41], s[50:51], 0, v[36:37]
	v_cndmask_b32_e64 v42, v51, v38, s[44:45]
	v_lshl_add_u64 v[38:39], s[46:47], 0, v[36:37]
	v_or_b32_e32 v36, 0x100, v36
	v_rsq_f32_e32 v51, v42
	v_lshl_add_u64 v[62:63], s[46:47], 0, v[34:35]
	v_lshl_add_u64 v[34:35], s[50:51], 0, v[34:35]
	global_load_dwordx4 v[46:49], v[38:39], off
	global_load_dwordx4 v[42:45], v[40:41], off
	v_lshl_add_u64 v[38:39], s[46:47], 0, v[36:37]
	v_lshl_add_u64 v[36:37], s[50:51], 0, v[36:37]
	global_load_dwordx4 v[62:65], v[62:63], off
	s_nop 0
	global_load_dwordx4 v[66:69], v[34:35], off
	s_nop 0
	global_load_dwordx4 v[38:41], v[38:39], off
	s_nop 0
	global_load_dwordx4 v[34:37], v[36:37], off
	v_mul_f32_e32 v70, 0x45800000, v51
	v_cndmask_b32_e64 v51, v51, v70, s[44:45]
	v_mul_f32_e64 v30, v51, -v30
	v_mul_f32_e64 v26, v51, -v26
	v_mul_f32_e64 v31, v51, -v31
	v_mul_f32_e64 v32, v51, -v32
	v_mul_f32_e64 v33, v51, -v33
	v_mul_f32_e64 v27, v51, -v27
	v_mul_f32_e64 v28, v51, -v28
	v_mul_f32_e32 v30, 0x3fb8aa3b, v30
	v_mul_f32_e32 v26, 0x3fb8aa3b, v26
	v_mul_f32_e32 v31, 0x3fb8aa3b, v31
	v_mul_f32_e32 v32, 0x3fb8aa3b, v32
	v_mul_f32_e32 v33, 0x3fb8aa3b, v33
	v_mul_f32_e32 v27, 0x3fb8aa3b, v27
	v_mul_f32_e32 v28, 0x3fb8aa3b, v28
	v_exp_f32_e32 v30, v30
	v_exp_f32_e32 v26, v26
	v_exp_f32_e32 v31, v31
	v_exp_f32_e32 v32, v32
	v_exp_f32_e32 v33, v33
	v_exp_f32_e32 v27, v27
	v_exp_f32_e32 v28, v28
	v_mul_f32_e64 v29, v51, -v29
	v_mul_f32_e32 v29, 0x3fb8aa3b, v29
	v_exp_f32_e32 v78, v29
	v_add_f32_e32 v29, 1.0, v30
	v_add_f32_e32 v30, 1.0, v26
	v_add_f32_e32 v31, 1.0, v31
	v_add_f32_e32 v32, 1.0, v32
	v_add_f32_e32 v33, 1.0, v33
	v_add_f32_e32 v70, 1.0, v27
	v_add_f32_e32 v71, 1.0, v28
	v_rcp_f32_e32 v26, v29
	v_rcp_f32_e32 v28, v30
	v_rcp_f32_e32 v27, v31
	v_rcp_f32_e32 v30, v32
	v_rcp_f32_e32 v31, v33
	v_rcp_f32_e32 v29, v70
	v_rcp_f32_e32 v32, v71
	v_mul_f32_e64 v18, v51, -v18
	v_mul_f32_e64 v20, v51, -v20
	v_add_f32_e32 v33, 1.0, v78
	v_mul_f32_e32 v18, 0x3fb8aa3b, v18
	v_mul_f32_e32 v20, 0x3fb8aa3b, v20
	v_rcp_f32_e32 v33, v33
	v_mul_f32_e64 v22, v51, -v22
	v_mul_f32_e64 v24, v51, -v24
	v_mul_f32_e32 v22, 0x3fb8aa3b, v22
	v_mul_f32_e32 v24, 0x3fb8aa3b, v24
	v_exp_f32_e32 v22, v22
	v_mul_f32_e64 v19, v51, -v19
	v_exp_f32_e32 v24, v24
	v_mul_f32_e64 v21, v51, -v21
	v_mul_f32_e32 v19, 0x3fb8aa3b, v19
	v_mul_f32_e32 v21, 0x3fb8aa3b, v21
	v_add_f32_e32 v22, 1.0, v22
	v_add_f32_e32 v24, 1.0, v24
	s_waitcnt vmcnt(7)
	v_lshlrev_b32_e32 v70, 16, v54
	v_and_b32_e32 v71, 0xffff0000, v54
	v_lshlrev_b32_e32 v54, 16, v55
	v_and_b32_e32 v55, 0xffff0000, v55
	s_waitcnt vmcnt(6)
	v_lshlrev_b32_e32 v74, 16, v58
	v_and_b32_e32 v75, 0xffff0000, v58
	v_lshlrev_b32_e32 v58, 16, v59
	v_and_b32_e32 v59, 0xffff0000, v59
	v_pk_fma_f32 v[30:31], v[30:31], v[58:59], v[54:55]
	v_pk_fma_f32 v[26:27], v[26:27], v[74:75], v[70:71]
	v_mul_f32_e32 v55, v31, v31
	v_mul_f32_e32 v54, v27, v27
	v_fmac_f32_e32 v54, v26, v26
	v_fmac_f32_e32 v55, v30, v30
	v_cvt_pk_bf16_f32 v26, v26, v27
	v_cvt_pk_bf16_f32 v27, v30, v31
	v_exp_f32_e32 v58, v18
	v_mul_f32_e64 v18, v51, -v23
	s_waitcnt vmcnt(3)
	v_lshlrev_b32_e32 v30, 16, v62
	v_and_b32_e32 v31, 0xffff0000, v62
	v_exp_f32_e32 v62, v20
	v_mul_f32_e64 v20, v51, -v25
	v_mul_f32_e32 v18, 0x3fb8aa3b, v18
	v_mul_f32_e32 v20, 0x3fb8aa3b, v20
	v_exp_f32_e32 v23, v18
	v_exp_f32_e32 v25, v20
	v_lshlrev_b32_e32 v72, 16, v56
	v_and_b32_e32 v73, 0xffff0000, v56
	v_lshlrev_b32_e32 v56, 16, v57
	v_and_b32_e32 v57, 0xffff0000, v57
	v_lshlrev_b32_e32 v76, 16, v60
	v_and_b32_e32 v77, 0xffff0000, v60
	v_lshlrev_b32_e32 v60, 16, v61
	v_and_b32_e32 v61, 0xffff0000, v61
	v_pk_fma_f32 v[32:33], v[32:33], v[60:61], v[56:57]
	v_exp_f32_e32 v60, v19
	v_exp_f32_e32 v51, v21
	v_add_f32_e32 v23, 1.0, v23
	v_add_f32_e32 v25, 1.0, v25
	v_rcp_f32_e32 v18, v22
	v_rcp_f32_e32 v19, v23
	v_rcp_f32_e32 v20, v24
	v_rcp_f32_e32 v21, v25
	v_pk_fma_f32 v[28:29], v[28:29], v[76:77], v[72:73]
	v_add_f32_e32 v22, 1.0, v58
	v_add_f32_e32 v23, 1.0, v60
	v_add_f32_e32 v24, 1.0, v62
	v_add_f32_e32 v25, 1.0, v51
	v_add_f32_e32 v54, v54, v55
	v_mul_f32_e32 v55, v29, v29
	v_mul_f32_e32 v56, v33, v33
	v_rcp_f32_e32 v22, v22
	v_rcp_f32_e32 v23, v23
	v_rcp_f32_e32 v24, v24
	v_rcp_f32_e32 v25, v25
	v_fmac_f32_e32 v55, v28, v28
	v_fmac_f32_e32 v56, v32, v32
	v_cvt_pk_bf16_f32 v28, v28, v29
	v_cvt_pk_bf16_f32 v29, v32, v33
	v_lshlrev_b32_e32 v32, 16, v63
	v_and_b32_e32 v33, 0xffff0000, v63
	s_waitcnt vmcnt(2)
	v_lshlrev_b32_e32 v58, 16, v66
	v_and_b32_e32 v59, 0xffff0000, v66
	v_lshlrev_b32_e32 v62, 16, v67
	v_and_b32_e32 v63, 0xffff0000, v67
	v_add_f32_e32 v55, v55, v56
	v_pk_fma_f32 v[32:33], v[20:21], v[62:63], v[32:33]
	v_pk_fma_f32 v[18:19], v[18:19], v[58:59], v[30:31]
	v_add_f32_e32 v70, v54, v55
	v_lshlrev_b32_e32 v54, 16, v64
	v_and_b32_e32 v55, 0xffff0000, v64
	v_lshlrev_b32_e32 v56, 16, v65
	v_and_b32_e32 v57, 0xffff0000, v65
	v_lshlrev_b32_e32 v60, 16, v68
	v_and_b32_e32 v61, 0xffff0000, v68
	v_lshlrev_b32_e32 v64, 16, v69
	v_and_b32_e32 v65, 0xffff0000, v69
	v_mul_f32_e32 v20, v19, v19
	v_mul_f32_e32 v21, v33, v33
	v_pk_fma_f32 v[24:25], v[24:25], v[64:65], v[56:57]
	v_pk_fma_f32 v[22:23], v[22:23], v[60:61], v[54:55]
	v_fmac_f32_e32 v20, v18, v18
	v_fmac_f32_e32 v21, v32, v32
	v_add_f32_e32 v20, v20, v21
	v_mul_f32_e32 v21, v23, v23
	v_mul_f32_e32 v30, v25, v25
	v_fmac_f32_e32 v21, v22, v22
	v_fmac_f32_e32 v30, v24, v24
	v_add_f32_e32 v21, v21, v30
	v_add_f32_e32 v20, v20, v21
	v_add_f32_e32 v51, v70, v20
	ds_bpermute_b32 v54, v213, v51
	v_lshlrev_b64 v[52:53], 11, v[168:169]
	v_lshl_add_u64 v[20:21], s[52:53], 0, v[52:53]
	v_lshl_add_u64 v[30:31], v[160:161], 1, v[20:21]
	global_store_dwordx4 v[30:31], v[26:29], off sc1
	v_cvt_pk_bf16_f32 v20, v18, v19
	s_waitcnt lgkmcnt(0)
	v_add_f32_e32 v18, v51, v54
	ds_bpermute_b32 v19, v212, v18
	v_cmp_gt_f32_e32 vcc, s31, v50
	v_cvt_pk_bf16_f32 v21, v32, v33
	v_cvt_pk_bf16_f32 v22, v22, v23
	v_cvt_pk_bf16_f32 v23, v24, v25
	global_store_dwordx4 v[30:31], v[20:23], off offset:256 sc1
	s_and_saveexec_b64 s[44:45], s[40:41]
	s_cbranch_execz .LBB0_1781
	v_lshl_add_u64 v[20:21], s[18:19], 0, v[166:167]
	v_lshl_add_u64 v[20:21], s[38:39], 2, v[20:21]
	s_lshl_b32 s48, s91, 2
	v_lshl_add_u64 v[20:21], v[20:21], 0, s[48:49]
	s_waitcnt lgkmcnt(0)
	v_add_f32_e32 v18, v18, v19
	global_store_dword v[20:21], v18, off
; __device__ __forceinline__ float bf_lo(unsigned w) { return __uint_as_float(w << 16); }
; __device__ __forceinline__ float bf_hi(unsigned w) { return __uint_as_float(w & 0xffff0000u); }
; __device__ __forceinline__ float dot4(f32x4 a) { return (a[0] * a[0] + a[1] * a[1]) + (a[2] * a[2] + a[3] * a[3]); }
; __device__ __forceinline__ float fq_sum(float s) { s += __shfl_xor(s, 16); s += __shfl_xor(s, 32); return s; }
;     __device__ __forceinline__ void operator()(const f32x4 (&acc)[2][2][4][2], const Unit& u, int wr, int wc, int fr, int fq) const {
;     ...
;             for (int k = 0; k < NB; ++k) {
;                 const int ai = (g * NB + k) >> 2, m = (g * NB + k) & 3;
;                 const int row = u.pm * 256 + ai * 128 + wr * 64 + m * 16 + fr;
;                 float ss = 0.f;
; #pragma unroll
;                 for (int bj = 0; bj < 2; ++bj) {
;                     const size_t off = (size_t)row * 1024 + colb + bj * 128;
;                     const u32x4 w = xw[k][bj];
;                     const f32x4 x0 = (f32x4){bf_lo(w.x), bf_hi(w.x), bf_lo(w.y), bf_hi(w.y)}, x1 = (f32x4){bf_lo(w.z), bf_hi(w.z), bf_lo(w.w), bf_hi(w.w)};
;                     f32x4 d0 = acc[ai][bj][m][0], d1 = acc[ai][bj][m][1];
;                     if (MODE == 2) { const float r2 = rs8[ai][m] * rs8[ai][m]; d0 = d0 * r2; d1 = d1 * r2; }
;                     if (MODE == 1) {
;                         const float rs = rs8[ai][m];
;                         const u32x4 q = pw[k][bj];
;                         const f32x4 p0 = (f32x4){bf_lo(q.x), bf_hi(q.x), bf_lo(q.y), bf_hi(q.y)}, p1 = (f32x4){bf_lo(q.z), bf_hi(q.z), bf_lo(q.w), bf_hi(q.w)};
; #pragma unroll
;                         for (int i = 0; i < 4; ++i) { d0[i] = p0[i] * __builtin_amdgcn_rcpf(1.0f + __expf(-d0[i] * rs)); d1[i] = p1[i] * __builtin_amdgcn_rcpf(1.0f + __expf(-d1[i] * rs)); }
;                     }
;                     const f32x4 y0 = x0 + d0, y1 = x1 + d1;
;                     if (LAST) { *(f32x4*)(xout + off) = y0; *(f32x4*)(xout + off + 4) = y1; }
;                     else { ss += dot4(y0) + dot4(y1); *(u32x4*)(xb + off) = pack8(y0, y1); }
;                 }
;                 if (!LAST) { ss = fq_sum(ss); if (fq == 0) xs_out[(size_t)row * 16 + u.pn * 4 + wc] = ss; }
;             }
.LBB0_1781:
	s_or_b64 exec, exec, s[44:45]
	v_mul_f32_e32 v18, 0x4b800000, v50
	v_cndmask_b32_e32 v18, v50, v18, vcc
	v_rsq_f32_e32 v22, v18
	v_lshlrev_b32_e32 v20, 16, v46
	v_and_b32_e32 v21, 0xffff0000, v46
	v_and_b32_e32 v29, 0xffff0000, v42
	v_mul_f32_e32 v23, 0x45800000, v22
	v_cndmask_b32_e32 v46, v22, v23, vcc
	v_mul_f32_e64 v10, v46, -v10
	v_mul_f32_e32 v10, 0x3fb8aa3b, v10
	v_mul_f32_e64 v14, v46, -v14
	v_exp_f32_e32 v28, v10
	v_mul_f32_e64 v10, v46, -v15
	v_mul_f32_e32 v14, 0x3fb8aa3b, v14
	v_mul_f32_e32 v10, 0x3fb8aa3b, v10
	v_mul_f32_e64 v11, v46, -v11
	v_exp_f32_e32 v14, v14
	v_exp_f32_e32 v15, v10
	v_mul_f32_e32 v11, 0x3fb8aa3b, v11
	v_mul_f32_e64 v12, v46, -v12
	v_exp_f32_e32 v30, v11
	v_mul_f32_e32 v12, 0x3fb8aa3b, v12
	v_mul_f32_e64 v16, v46, -v16
	v_exp_f32_e32 v32, v12
	v_mul_f32_e64 v12, v46, -v17
	v_mul_f32_e32 v16, 0x3fb8aa3b, v16
	v_mul_f32_e32 v12, 0x3fb8aa3b, v12
	v_mul_f32_e64 v13, v46, -v13
	v_add_f32_e32 v14, 1.0, v14
	v_add_f32_e32 v15, 1.0, v15
	v_exp_f32_e32 v16, v16
	v_exp_f32_e32 v17, v12
	v_mul_f32_e32 v13, 0x3fb8aa3b, v13
	v_rcp_f32_e32 v10, v14
	v_add_f32_e32 v14, 1.0, v28
	v_rcp_f32_e32 v11, v15
	v_lshlrev_b32_e32 v28, 16, v42
	v_add_f32_e32 v15, 1.0, v30
	v_exp_f32_e32 v42, v13
	v_rcp_f32_e32 v14, v14
	v_rcp_f32_e32 v15, v15
	v_add_f32_e32 v16, 1.0, v16
	v_add_f32_e32 v17, 1.0, v17
	v_mul_f32_e64 v2, v46, -v2
	v_mul_f32_e64 v4, v46, -v4
	v_lshlrev_b32_e32 v24, 16, v48
	v_and_b32_e32 v25, 0xffff0000, v48
	v_lshlrev_b32_e32 v30, 16, v44
	v_and_b32_e32 v31, 0xffff0000, v44
	v_rcp_f32_e32 v12, v16
	v_add_f32_e32 v16, 1.0, v32
	v_rcp_f32_e32 v13, v17
	v_add_f32_e32 v17, 1.0, v42
	v_mul_f32_e32 v2, 0x3fb8aa3b, v2
	v_mul_f32_e32 v4, 0x3fb8aa3b, v4
	v_rcp_f32_e32 v16, v16
	v_rcp_f32_e32 v17, v17
	v_pk_fma_f32 v[10:11], v[10:11], v[28:29], v[20:21]
	v_pk_fma_f32 v[14:15], v[14:15], v[30:31], v[24:25]
	v_mul_f32_e64 v6, v46, -v6
	v_exp_f32_e32 v24, v2
	v_mul_f32_e64 v2, v46, -v7
	v_mul_f32_e64 v8, v46, -v8
	v_exp_f32_e32 v28, v4
	v_mul_f32_e64 v4, v46, -v9
	v_mul_f32_e32 v6, 0x3fb8aa3b, v6
	v_mul_f32_e32 v2, 0x3fb8aa3b, v2
	v_mul_f32_e32 v8, 0x3fb8aa3b, v8
	v_mul_f32_e32 v4, 0x3fb8aa3b, v4
	v_exp_f32_e32 v6, v6
	v_exp_f32_e32 v7, v2
	v_mul_f32_e64 v3, v46, -v3
	v_exp_f32_e32 v8, v8
	v_exp_f32_e32 v9, v4
	v_mul_f32_e64 v5, v46, -v5
	v_lshlrev_b32_e32 v26, 16, v49
	v_and_b32_e32 v27, 0xffff0000, v49
	v_lshlrev_b32_e32 v32, 16, v43
	v_and_b32_e32 v33, 0xffff0000, v43
	v_lshlrev_b32_e32 v42, 16, v45
	v_and_b32_e32 v43, 0xffff0000, v45
	v_mul_f32_e32 v3, 0x3fb8aa3b, v3
	v_mul_f32_e32 v5, 0x3fb8aa3b, v5
	v_pk_fma_f32 v[16:17], v[16:17], v[42:43], v[26:27]
	v_exp_f32_e32 v26, v3
	v_exp_f32_e32 v30, v5
	v_lshlrev_b32_e32 v22, 16, v47
	v_and_b32_e32 v23, 0xffff0000, v47
	v_pk_fma_f32 v[12:13], v[12:13], v[32:33], v[22:23]
	v_add_f32_e32 v6, 1.0, v6
	v_add_f32_e32 v7, 1.0, v7
	v_add_f32_e32 v8, 1.0, v8
	v_add_f32_e32 v9, 1.0, v9
	v_mul_f32_e32 v20, v11, v11
	v_mul_f32_e32 v21, v13, v13
	v_rcp_f32_e32 v2, v6
	v_rcp_f32_e32 v3, v7
	v_rcp_f32_e32 v4, v8
	v_rcp_f32_e32 v5, v9
	v_fmac_f32_e32 v20, v10, v10
	v_fmac_f32_e32 v21, v12, v12
	v_add_f32_e32 v6, 1.0, v24
	v_add_f32_e32 v7, 1.0, v26
	v_add_f32_e32 v8, 1.0, v28
	v_add_f32_e32 v9, 1.0, v30
	v_add_f32_e32 v20, v20, v21
	v_mul_f32_e32 v21, v15, v15
	v_mul_f32_e32 v22, v17, v17
	v_rcp_f32_e32 v6, v6
	v_rcp_f32_e32 v7, v7
	v_rcp_f32_e32 v8, v8
	v_rcp_f32_e32 v9, v9
	v_fmac_f32_e32 v21, v14, v14
	v_fmac_f32_e32 v22, v16, v16
	v_cvt_pk_bf16_f32 v10, v10, v11
	v_cvt_pk_bf16_f32 v11, v12, v13
	v_cvt_pk_bf16_f32 v12, v14, v15
	v_cvt_pk_bf16_f32 v13, v16, v17
	s_waitcnt vmcnt(3)
	v_lshlrev_b32_e32 v14, 16, v38
	v_and_b32_e32 v15, 0xffff0000, v38
	v_lshlrev_b32_e32 v16, 16, v39
	v_and_b32_e32 v17, 0xffff0000, v39
	s_waitcnt vmcnt(2)
	v_lshlrev_b32_e32 v24, 16, v34
	v_and_b32_e32 v25, 0xffff0000, v34
	v_lshlrev_b32_e32 v28, 16, v35
	v_and_b32_e32 v29, 0xffff0000, v35
	v_add_f32_e32 v21, v21, v22
	v_pk_fma_f32 v[16:17], v[4:5], v[28:29], v[16:17]
	v_pk_fma_f32 v[2:3], v[2:3], v[24:25], v[14:15]
	v_add_f32_e32 v32, v20, v21
	v_lshlrev_b32_e32 v20, 16, v40
	v_and_b32_e32 v21, 0xffff0000, v40
	v_lshlrev_b32_e32 v22, 16, v41
	v_and_b32_e32 v23, 0xffff0000, v41
	v_lshlrev_b32_e32 v26, 16, v36
	v_and_b32_e32 v27, 0xffff0000, v36
	v_lshlrev_b32_e32 v30, 16, v37
	v_and_b32_e32 v31, 0xffff0000, v37
	v_mul_f32_e32 v4, v3, v3
	v_mul_f32_e32 v5, v17, v17
	v_pk_fma_f32 v[8:9], v[8:9], v[30:31], v[22:23]
	v_pk_fma_f32 v[6:7], v[6:7], v[26:27], v[20:21]
	v_fmac_f32_e32 v4, v2, v2
	v_fmac_f32_e32 v5, v16, v16
	v_add_f32_e32 v4, v4, v5
	v_mul_f32_e32 v5, v7, v7
	v_mul_f32_e32 v14, v9, v9
	v_fmac_f32_e32 v5, v6, v6
	v_fmac_f32_e32 v14, v8, v8
	v_add_f32_e32 v5, v5, v14
	v_add_f32_e32 v4, v4, v5
	v_add_f32_e32 v20, v32, v4
	ds_bpermute_b32 v21, v213, v20
	s_waitcnt lgkmcnt(1)
	v_lshlrev_b64 v[18:19], 11, v[164:165]
	v_lshl_add_u64 v[4:5], s[52:53], 0, v[18:19]
	v_lshl_add_u64 v[14:15], v[160:161], 1, v[4:5]
	global_store_dwordx4 v[14:15], v[10:13], off sc1
	v_cvt_pk_bf16_f32 v4, v2, v3
	s_waitcnt lgkmcnt(0)
	v_add_f32_e32 v2, v20, v21
	ds_bpermute_b32 v3, v212, v2
	v_cvt_pk_bf16_f32 v5, v16, v17
	v_cvt_pk_bf16_f32 v6, v6, v7
	v_cvt_pk_bf16_f32 v7, v8, v9
	global_store_dwordx4 v[14:15], v[4:7], off offset:256 sc1
	s_and_saveexec_b64 s[44:45], s[40:41]
	s_cbranch_execz .LBB0_1783
	v_lshl_add_u64 v[4:5], s[18:19], 0, v[158:159]
	v_lshl_add_u64 v[4:5], s[38:39], 2, v[4:5]
	s_lshl_b32 s48, s91, 2
	v_lshl_add_u64 v[4:5], v[4:5], 0, s[48:49]
	s_waitcnt lgkmcnt(0)
	v_add_f32_e32 v2, v2, v3
	global_store_dword v[4:5], v2, off
